# fix-up passes P3/P9 run only on the WGs with slack in the next GEMM (its weight-converter WGs), all other WGs skip them; row-tile-32 consumers poll the counter late in the K-loop of the preceding unit
# speedup vs baseline: 1.0158x; 1.0019x over previous
; __device__ __forceinline__ float bf_lo(unsigned w) { return __uint_as_float(w << 16); }
; __device__ __forceinline__ float bf_hi(unsigned w) { return __uint_as_float(w & 0xffff0000u); }
; template <int MODE> __device__ __forceinline__ void fix_resid(const float* part, int nsl, const float* xp, const float* xs, const float* meta, float* xbuf, bf16_t* xb, float* ss, float* out, int gw, int ngw, int lane) {
;     for (int it = gw; it < NTAIL * 8; it += ngw) {
;         const int rloc = it >> 3, row = TAIL0 + rloc, col = (it & 7) * 256 + lane * 4;
;         const bf16_t* p = (const bf16_t*)part + (size_t)rloc * 2048 + col;
;         f32x4_t v = (f32x4_t){0.f, 0.f, 0.f, 0.f};
; #pragma unroll 8
;         for (int s = 0; s < nsl; ++s) { const u32x2_t w = __builtin_nontemporal_load((const u32x2_t*)(p + (size_t)s * (256 * 2048))); v += (f32x4_t){bf_lo(w.x), bf_hi(w.x), bf_lo(w.y), bf_hi(w.y)}; }
;         const float scale = (MODE == 1) ? 1.0f : 0.5f;
;         const u32x2_t bw = *(const u32x2_t*)(xb + (size_t)row * DM + col);
.LBB0_442:
	s_cmp_lt_i32 s66, 4
	s_cselect_b64 s[6:7], -1, 0
	s_and_b64 s[0:1], s[6:7], s[0:1]
	s_cmpk_lt_i32 s83, 0x600
	s_cselect_b64 s[6:7], -1, 0
	v_writelane_b32 v251, s6, 63
	v_lshlrev_b32_e32 v241, 2, v202
	v_mbcnt_lo_u32_b32 v201, -1, 0
	v_writelane_b32 v250, s7, 0
	s_cmpk_gt_u32 s33, 223
	s_cselect_b64 s[6:7], -1, 0
	s_and_b64 s[6:7], s[0:1], s[6:7]
	s_andn2_b64 vcc, exec, s[6:7]
	s_cbranch_vccnz .LBB0_452
	v_readlane_b32 s6, v251, 29
	v_mbcnt_hi_u32_b32 v10, -1, v201
	s_sub_i32 s2, s33, 224
	s_lshl_b32 s2, s2, 11
	s_lshl_b32 s6, s6, 8
	v_and_b32_e32 v0, 64, v10
	s_add_i32 s2, s2, s6
	s_mov_b32 s10, 0x10000
	s_waitcnt lgkmcnt(0)
	v_mov_b32_e32 v1, 0
	s_mov_b32 s12, 0x600000
	s_mov_b32 s13, 0x700000
	v_add_u32_e32 v11, 64, v0
	v_xor_b32_e32 v12, 1, v10
	v_xor_b32_e32 v13, 2, v10
	v_xor_b32_e32 v14, 4, v10
	v_xor_b32_e32 v15, 8, v10
	v_xor_b32_e32 v16, 16, v10
	v_xor_b32_e32 v17, 32, v10
	s_lshr_b32 s14, s2, 8
	s_branch .LBB0_445
.LBB0_444:
	s_or_b64 exec, exec, s[18:19]
	s_addk_i32 s14, 0x100
	s_add_i32 s2, s2, s10
	s_cmpk_lt_i32 s14, 0x600
	s_cbranch_scc0 .LBB0_452
.LBB0_445:
	s_lshl_b32 s6, s2, 1
	s_and_b32 s6, s6, 0xe00
	v_lshl_or_b32 v0, v241, 1, s6
	s_ashr_i32 s6, s14, 3
	s_ashr_i32 s7, s6, 31
	s_lshl_b64 s[18:19], s[6:7], 12
	s_add_u32 s18, s86, s18
	s_addc_u32 s19, s87, s19
	s_waitcnt lgkmcnt(0)
	v_mov_b32_e32 v6, 0
	v_mov_b32_e32 v7, v1
	v_mov_b32_e32 v8, 0
	v_mov_b32_e32 v9, v1
	global_load_dwordx2 v[32:33], v0, s[18:19] nt
	s_add_u32 s18, s18, 0x100000
	s_addc_u32 s19, s19, 0
	global_load_dwordx2 v[34:35], v0, s[18:19] nt
	s_add_u32 s18, s18, 0x100000
	s_addc_u32 s19, s19, 0
	global_load_dwordx2 v[36:37], v0, s[18:19] nt
	s_add_u32 s18, s18, 0x100000
	s_addc_u32 s19, s19, 0
	global_load_dwordx2 v[38:39], v0, s[18:19] nt
	s_add_u32 s18, s18, 0x100000
	s_addc_u32 s19, s19, 0
	global_load_dwordx2 v[40:41], v0, s[18:19] nt
	s_add_u32 s18, s18, 0x100000
	s_addc_u32 s19, s19, 0
	global_load_dwordx2 v[42:43], v0, s[18:19] nt
	s_add_u32 s18, s18, 0x100000
	s_addc_u32 s19, s19, 0
	global_load_dwordx2 v[44:45], v0, s[18:19] nt
	s_add_u32 s18, s18, 0x100000
	s_addc_u32 s19, s19, 0
	global_load_dwordx2 v[46:47], v0, s[18:19] nt
	s_add_u32 s18, s18, 0x100000
	s_addc_u32 s19, s19, 0
	global_load_dwordx2 v[48:49], v0, s[18:19] nt
	s_add_u32 s18, s18, 0x100000
	s_addc_u32 s19, s19, 0
	global_load_dwordx2 v[50:51], v0, s[18:19] nt
	s_add_u32 s18, s18, 0x100000
	s_addc_u32 s19, s19, 0
	global_load_dwordx2 v[52:53], v0, s[18:19] nt
	s_add_u32 s18, s18, 0x100000
	s_addc_u32 s19, s19, 0
	global_load_dwordx2 v[54:55], v0, s[18:19] nt
	s_add_u32 s18, s18, 0x100000
	s_addc_u32 s19, s19, 0
	global_load_dwordx2 v[56:57], v0, s[18:19] nt
	s_add_u32 s18, s18, 0x100000
	s_addc_u32 s19, s19, 0
	global_load_dwordx2 v[58:59], v0, s[18:19] nt
	s_add_u32 s18, s18, 0x100000
	s_addc_u32 s19, s19, 0
	global_load_dwordx2 v[60:61], v0, s[18:19] nt
	s_add_u32 s18, s18, 0x100000
	s_addc_u32 s19, s19, 0
	global_load_dwordx2 v[62:63], v0, s[18:19] nt
	s_add_u32 s18, s18, 0x100000
	s_addc_u32 s19, s19, 0
	global_load_dwordx2 v[64:65], v0, s[18:19] nt
	s_add_u32 s18, s18, 0x100000
	s_addc_u32 s19, s19, 0
	global_load_dwordx2 v[66:67], v0, s[18:19] nt
	s_add_u32 s18, s18, 0x100000
	s_addc_u32 s19, s19, 0
	global_load_dwordx2 v[68:69], v0, s[18:19] nt
	s_add_u32 s18, s18, 0x100000
	s_addc_u32 s19, s19, 0
	global_load_dwordx2 v[70:71], v0, s[18:19] nt
	s_add_u32 s18, s18, 0x100000
	s_addc_u32 s19, s19, 0
	global_load_dwordx2 v[72:73], v0, s[18:19] nt
	s_add_u32 s18, s18, 0x100000
	s_addc_u32 s19, s19, 0
	global_load_dwordx2 v[74:75], v0, s[18:19] nt
	s_add_u32 s18, s18, 0x100000
	s_addc_u32 s19, s19, 0
	global_load_dwordx2 v[76:77], v0, s[18:19] nt
	s_add_u32 s18, s18, 0x100000
	s_addc_u32 s19, s19, 0
	global_load_dwordx2 v[78:79], v0, s[18:19] nt
	s_add_u32 s18, s18, 0x100000
	s_addc_u32 s19, s19, 0
	global_load_dwordx2 v[80:81], v0, s[18:19] nt
	s_add_u32 s18, s18, 0x100000
	s_addc_u32 s19, s19, 0
	global_load_dwordx2 v[82:83], v0, s[18:19] nt
	s_add_u32 s18, s18, 0x100000
	s_addc_u32 s19, s19, 0
	global_load_dwordx2 v[84:85], v0, s[18:19] nt
	s_add_u32 s18, s18, 0x100000
	s_addc_u32 s19, s19, 0
	global_load_dwordx2 v[86:87], v0, s[18:19] nt
	s_add_u32 s18, s18, 0x100000
	s_addc_u32 s19, s19, 0
	global_load_dwordx2 v[88:89], v0, s[18:19] nt
	s_add_u32 s18, s18, 0x100000
	s_addc_u32 s19, s19, 0
	global_load_dwordx2 v[90:91], v0, s[18:19] nt
	s_add_u32 s18, s18, 0x100000
	s_addc_u32 s19, s19, 0
	global_load_dwordx2 v[92:93], v0, s[18:19] nt
	s_add_u32 s18, s18, 0x100000
	s_addc_u32 s19, s19, 0
	global_load_dwordx2 v[94:95], v0, s[18:19] nt
	s_lshl_b32 s7, s14, 8
	s_and_b32 s7, s7, 0x700
	s_addk_i32 s6, 0x2000
	v_or_b32_e32 v0, s7, v241
	s_ashr_i32 s7, s6, 31
	s_lshl_b64 s[18:19], s[6:7], 12
	s_add_u32 s18, s96, s18
	s_addc_u32 s19, s97, s19
	v_lshlrev_b32_e32 v0, 1, v0
	global_load_dwordx2 v[2:3], v0, s[18:19]
	s_waitcnt vmcnt(25)
; __device__ __forceinline__ float bf_lo(unsigned w) { return __uint_as_float(w << 16); }
; __device__ __forceinline__ float bf_hi(unsigned w) { return __uint_as_float(w & 0xffff0000u); }
; template <int MODE> __device__ __forceinline__ void fix_resid(const float* part, int nsl, const float* xp, const float* xs, const float* meta, float* xbuf, bf16_t* xb, float* ss, float* out, int gw, int ngw, int lane) {
;     ...
;         f32x4_t v = (f32x4_t){0.f, 0.f, 0.f, 0.f};
; #pragma unroll 8
;         for (int s = 0; s < nsl; ++s) { const u32x2_t w = __builtin_nontemporal_load((const u32x2_t*)(p + (size_t)s * (256 * 2048))); v += (f32x4_t){bf_lo(w.x), bf_hi(w.x), bf_lo(w.y), bf_hi(w.y)}; }
;         const float scale = (MODE == 1) ? 1.0f : 0.5f;
	v_lshlrev_b32_e32 v20, 16, v32
	v_and_b32_e32 v21, 0xffff0000, v32
	v_lshlrev_b32_e32 v18, 16, v33
	v_and_b32_e32 v19, 0xffff0000, v33
	v_pk_add_f32 v[8:9], v[8:9], v[18:19]
	v_pk_add_f32 v[6:7], v[6:7], v[20:21]
	v_lshlrev_b32_e32 v20, 16, v34
	v_and_b32_e32 v21, 0xffff0000, v34
	v_lshlrev_b32_e32 v18, 16, v35
	v_and_b32_e32 v19, 0xffff0000, v35
	v_pk_add_f32 v[8:9], v[8:9], v[18:19]
	v_pk_add_f32 v[6:7], v[6:7], v[20:21]
	v_lshlrev_b32_e32 v20, 16, v36
	v_and_b32_e32 v21, 0xffff0000, v36
	v_lshlrev_b32_e32 v18, 16, v37
	v_and_b32_e32 v19, 0xffff0000, v37
	v_pk_add_f32 v[8:9], v[8:9], v[18:19]
	v_pk_add_f32 v[6:7], v[6:7], v[20:21]
	v_lshlrev_b32_e32 v20, 16, v38
	v_and_b32_e32 v21, 0xffff0000, v38
	v_lshlrev_b32_e32 v18, 16, v39
	v_and_b32_e32 v19, 0xffff0000, v39
	v_pk_add_f32 v[8:9], v[8:9], v[18:19]
	v_pk_add_f32 v[6:7], v[6:7], v[20:21]
	v_lshlrev_b32_e32 v20, 16, v40
	v_and_b32_e32 v21, 0xffff0000, v40
	v_lshlrev_b32_e32 v18, 16, v41
	v_and_b32_e32 v19, 0xffff0000, v41
	v_pk_add_f32 v[8:9], v[8:9], v[18:19]
	v_pk_add_f32 v[6:7], v[6:7], v[20:21]
	v_lshlrev_b32_e32 v20, 16, v42
	v_and_b32_e32 v21, 0xffff0000, v42
	v_lshlrev_b32_e32 v18, 16, v43
	v_and_b32_e32 v19, 0xffff0000, v43
	v_pk_add_f32 v[8:9], v[8:9], v[18:19]
	v_pk_add_f32 v[6:7], v[6:7], v[20:21]
	v_lshlrev_b32_e32 v20, 16, v44
	v_and_b32_e32 v21, 0xffff0000, v44
	v_lshlrev_b32_e32 v18, 16, v45
	v_and_b32_e32 v19, 0xffff0000, v45
	v_pk_add_f32 v[8:9], v[8:9], v[18:19]
	v_pk_add_f32 v[6:7], v[6:7], v[20:21]
	v_lshlrev_b32_e32 v20, 16, v46
	v_and_b32_e32 v21, 0xffff0000, v46
	v_lshlrev_b32_e32 v18, 16, v47
	v_and_b32_e32 v19, 0xffff0000, v47
	v_pk_add_f32 v[8:9], v[8:9], v[18:19]
	v_pk_add_f32 v[6:7], v[6:7], v[20:21]
	s_waitcnt vmcnt(17)
	v_lshlrev_b32_e32 v20, 16, v48
	v_and_b32_e32 v21, 0xffff0000, v48
	v_lshlrev_b32_e32 v18, 16, v49
	v_and_b32_e32 v19, 0xffff0000, v49
	v_pk_add_f32 v[8:9], v[8:9], v[18:19]
	v_pk_add_f32 v[6:7], v[6:7], v[20:21]
	v_lshlrev_b32_e32 v20, 16, v50
	v_and_b32_e32 v21, 0xffff0000, v50
	v_lshlrev_b32_e32 v18, 16, v51
	v_and_b32_e32 v19, 0xffff0000, v51
	v_pk_add_f32 v[8:9], v[8:9], v[18:19]
	v_pk_add_f32 v[6:7], v[6:7], v[20:21]
	v_lshlrev_b32_e32 v20, 16, v52
	v_and_b32_e32 v21, 0xffff0000, v52
	v_lshlrev_b32_e32 v18, 16, v53
	v_and_b32_e32 v19, 0xffff0000, v53
	v_pk_add_f32 v[8:9], v[8:9], v[18:19]
	v_pk_add_f32 v[6:7], v[6:7], v[20:21]
	v_lshlrev_b32_e32 v20, 16, v54
	v_and_b32_e32 v21, 0xffff0000, v54
	v_lshlrev_b32_e32 v18, 16, v55
	v_and_b32_e32 v19, 0xffff0000, v55
	v_pk_add_f32 v[8:9], v[8:9], v[18:19]
	v_pk_add_f32 v[6:7], v[6:7], v[20:21]
	v_lshlrev_b32_e32 v20, 16, v56
	v_and_b32_e32 v21, 0xffff0000, v56
	v_lshlrev_b32_e32 v18, 16, v57
	v_and_b32_e32 v19, 0xffff0000, v57
	v_pk_add_f32 v[8:9], v[8:9], v[18:19]
	v_pk_add_f32 v[6:7], v[6:7], v[20:21]
	v_lshlrev_b32_e32 v20, 16, v58
	v_and_b32_e32 v21, 0xffff0000, v58
	v_lshlrev_b32_e32 v18, 16, v59
	v_and_b32_e32 v19, 0xffff0000, v59
	v_pk_add_f32 v[8:9], v[8:9], v[18:19]
	v_pk_add_f32 v[6:7], v[6:7], v[20:21]
	v_lshlrev_b32_e32 v20, 16, v60
	v_and_b32_e32 v21, 0xffff0000, v60
	v_lshlrev_b32_e32 v18, 16, v61
	v_and_b32_e32 v19, 0xffff0000, v61
	v_pk_add_f32 v[8:9], v[8:9], v[18:19]
	v_pk_add_f32 v[6:7], v[6:7], v[20:21]
	v_lshlrev_b32_e32 v20, 16, v62
	v_and_b32_e32 v21, 0xffff0000, v62
	v_lshlrev_b32_e32 v18, 16, v63
	v_and_b32_e32 v19, 0xffff0000, v63
	v_pk_add_f32 v[8:9], v[8:9], v[18:19]
	v_pk_add_f32 v[6:7], v[6:7], v[20:21]
	s_waitcnt vmcnt(9)
	v_lshlrev_b32_e32 v20, 16, v64
	v_and_b32_e32 v21, 0xffff0000, v64
	v_lshlrev_b32_e32 v18, 16, v65
	v_and_b32_e32 v19, 0xffff0000, v65
	v_pk_add_f32 v[8:9], v[8:9], v[18:19]
	v_pk_add_f32 v[6:7], v[6:7], v[20:21]
	v_lshlrev_b32_e32 v20, 16, v66
	v_and_b32_e32 v21, 0xffff0000, v66
	v_lshlrev_b32_e32 v18, 16, v67
	v_and_b32_e32 v19, 0xffff0000, v67
	v_pk_add_f32 v[8:9], v[8:9], v[18:19]
	v_pk_add_f32 v[6:7], v[6:7], v[20:21]
	v_lshlrev_b32_e32 v20, 16, v68
	v_and_b32_e32 v21, 0xffff0000, v68
	v_lshlrev_b32_e32 v18, 16, v69
	v_and_b32_e32 v19, 0xffff0000, v69
	v_pk_add_f32 v[8:9], v[8:9], v[18:19]
	v_pk_add_f32 v[6:7], v[6:7], v[20:21]
	v_lshlrev_b32_e32 v20, 16, v70
	v_and_b32_e32 v21, 0xffff0000, v70
	v_lshlrev_b32_e32 v18, 16, v71
	v_and_b32_e32 v19, 0xffff0000, v71
	v_pk_add_f32 v[8:9], v[8:9], v[18:19]
	v_pk_add_f32 v[6:7], v[6:7], v[20:21]
	v_lshlrev_b32_e32 v20, 16, v72
	v_and_b32_e32 v21, 0xffff0000, v72
	v_lshlrev_b32_e32 v18, 16, v73
	v_and_b32_e32 v19, 0xffff0000, v73
	v_pk_add_f32 v[8:9], v[8:9], v[18:19]
	v_pk_add_f32 v[6:7], v[6:7], v[20:21]
	v_lshlrev_b32_e32 v20, 16, v74
	v_and_b32_e32 v21, 0xffff0000, v74
	v_lshlrev_b32_e32 v18, 16, v75
	v_and_b32_e32 v19, 0xffff0000, v75
	v_pk_add_f32 v[8:9], v[8:9], v[18:19]
	v_pk_add_f32 v[6:7], v[6:7], v[20:21]
	v_lshlrev_b32_e32 v20, 16, v76
	v_and_b32_e32 v21, 0xffff0000, v76
	v_lshlrev_b32_e32 v18, 16, v77
	v_and_b32_e32 v19, 0xffff0000, v77
	v_pk_add_f32 v[8:9], v[8:9], v[18:19]
	v_pk_add_f32 v[6:7], v[6:7], v[20:21]
	v_lshlrev_b32_e32 v20, 16, v78
	v_and_b32_e32 v21, 0xffff0000, v78
	v_lshlrev_b32_e32 v18, 16, v79
	v_and_b32_e32 v19, 0xffff0000, v79
	v_pk_add_f32 v[8:9], v[8:9], v[18:19]
	v_pk_add_f32 v[6:7], v[6:7], v[20:21]
	s_waitcnt vmcnt(1)
; __device__ __forceinline__ float bf_lo(unsigned w) { return __uint_as_float(w << 16); }
; __device__ __forceinline__ float bf_hi(unsigned w) { return __uint_as_float(w & 0xffff0000u); }
; __device__ __forceinline__ unsigned pk2(float lo, float hi) { return pg8::cvt_pk_bf16(lo, hi); }
; template <int MODE> __device__ __forceinline__ void fix_resid(const float* part, int nsl, const float* xp, const float* xs, const float* meta, float* xbuf, bf16_t* xb, float* ss, float* out, int gw, int ngw, int lane) {
;     ...
;         for (int s = 0; s < nsl; ++s) { const u32x2_t w = __builtin_nontemporal_load((const u32x2_t*)(p + (size_t)s * (256 * 2048))); v += (f32x4_t){bf_lo(w.x), bf_hi(w.x), bf_lo(w.y), bf_hi(w.y)}; }
;         const float scale = (MODE == 1) ? 1.0f : 0.5f;
;         const u32x2_t bw = *(const u32x2_t*)(xb + (size_t)row * DM + col);
;         const f32x4_t o = (f32x4_t){bf_lo(bw.x), bf_hi(bw.x), bf_lo(bw.y), bf_hi(bw.y)} + v * scale;
;         if (MODE == 2) { float* dst = y_row(out, row); if (dst) __builtin_nontemporal_store(o, (f32x4_t*)(dst + col)); }
;         else {
;             u32x2_t w; w.x = pk2(o.x, o.y); w.y = pk2(o.z, o.w); *(u32x2_t*)(xb + (size_t)row * DM + col) = w;
;             const float sq = wave_sum((o.x * o.x + o.y * o.y) + (o.z * o.z + o.w * o.w));
;             if (lane == 0) __hip_atomic_fetch_add(ss + row, sq, __ATOMIC_RELAXED, __HIP_MEMORY_SCOPE_AGENT);
;         }
	v_lshlrev_b32_e32 v20, 16, v80
	v_and_b32_e32 v21, 0xffff0000, v80
	v_lshlrev_b32_e32 v18, 16, v81
	v_and_b32_e32 v19, 0xffff0000, v81
	v_pk_add_f32 v[8:9], v[8:9], v[18:19]
	v_pk_add_f32 v[6:7], v[6:7], v[20:21]
	v_lshlrev_b32_e32 v20, 16, v82
	v_and_b32_e32 v21, 0xffff0000, v82
	v_lshlrev_b32_e32 v18, 16, v83
	v_and_b32_e32 v19, 0xffff0000, v83
	v_pk_add_f32 v[8:9], v[8:9], v[18:19]
	v_pk_add_f32 v[6:7], v[6:7], v[20:21]
	v_lshlrev_b32_e32 v20, 16, v84
	v_and_b32_e32 v21, 0xffff0000, v84
	v_lshlrev_b32_e32 v18, 16, v85
	v_and_b32_e32 v19, 0xffff0000, v85
	v_pk_add_f32 v[8:9], v[8:9], v[18:19]
	v_pk_add_f32 v[6:7], v[6:7], v[20:21]
	v_lshlrev_b32_e32 v20, 16, v86
	v_and_b32_e32 v21, 0xffff0000, v86
	v_lshlrev_b32_e32 v18, 16, v87
	v_and_b32_e32 v19, 0xffff0000, v87
	v_pk_add_f32 v[8:9], v[8:9], v[18:19]
	v_pk_add_f32 v[6:7], v[6:7], v[20:21]
	v_lshlrev_b32_e32 v20, 16, v88
	v_and_b32_e32 v21, 0xffff0000, v88
	v_lshlrev_b32_e32 v18, 16, v89
	v_and_b32_e32 v19, 0xffff0000, v89
	v_pk_add_f32 v[8:9], v[8:9], v[18:19]
	v_pk_add_f32 v[6:7], v[6:7], v[20:21]
	v_lshlrev_b32_e32 v20, 16, v90
	v_and_b32_e32 v21, 0xffff0000, v90
	v_lshlrev_b32_e32 v18, 16, v91
	v_and_b32_e32 v19, 0xffff0000, v91
	v_pk_add_f32 v[8:9], v[8:9], v[18:19]
	v_pk_add_f32 v[6:7], v[6:7], v[20:21]
	v_lshlrev_b32_e32 v20, 16, v92
	v_and_b32_e32 v21, 0xffff0000, v92
	v_lshlrev_b32_e32 v18, 16, v93
	v_and_b32_e32 v19, 0xffff0000, v93
	v_pk_add_f32 v[8:9], v[8:9], v[18:19]
	v_pk_add_f32 v[6:7], v[6:7], v[20:21]
	v_lshlrev_b32_e32 v20, 16, v94
	v_and_b32_e32 v21, 0xffff0000, v94
	v_lshlrev_b32_e32 v18, 16, v95
	v_and_b32_e32 v19, 0xffff0000, v95
	v_pk_add_f32 v[8:9], v[8:9], v[18:19]
	v_pk_add_f32 v[6:7], v[6:7], v[20:21]
	v_cmp_lt_i32_e32 vcc, v12, v11
	s_waitcnt vmcnt(0)
	v_lshlrev_b32_e32 v4, 16, v2
	v_and_b32_e32 v5, 0xffff0000, v2
	v_lshlrev_b32_e32 v2, 16, v3
	v_and_b32_e32 v3, 0xffff0000, v3
	v_pk_fma_f32 v[2:3], v[8:9], 0.5, v[2:3] op_sel_hi:[1,0,1]
	v_pk_fma_f32 v[4:5], v[6:7], 0.5, v[4:5] op_sel_hi:[1,0,1]
	s_nop 0
	v_cvt_pk_bf16_f32 v6, v4, v5
	v_cvt_pk_bf16_f32 v7, v2, v3
	global_store_dwordx2 v0, v[6:7], s[18:19] sc0 sc1
	v_mul_f32_e32 v0, v5, v5
	v_mul_f32_e32 v3, v3, v3
	v_fmac_f32_e32 v0, v4, v4
	v_fmac_f32_e32 v3, v2, v2
	v_cndmask_b32_e32 v2, v10, v12, vcc
	v_add_f32_e32 v0, v0, v3
	v_lshlrev_b32_e32 v2, 2, v2
	ds_bpermute_b32 v2, v2, v0
	v_cmp_lt_i32_e32 vcc, v13, v11
	s_waitcnt lgkmcnt(0)
	v_add_f32_e32 v0, v0, v2
	v_cndmask_b32_e32 v2, v10, v13, vcc
	v_lshlrev_b32_e32 v2, 2, v2
	ds_bpermute_b32 v2, v2, v0
	v_cmp_lt_i32_e32 vcc, v14, v11
	s_waitcnt lgkmcnt(0)
	v_add_f32_e32 v0, v0, v2
	v_cndmask_b32_e32 v2, v10, v14, vcc
	v_lshlrev_b32_e32 v2, 2, v2
	ds_bpermute_b32 v2, v2, v0
	v_cmp_lt_i32_e32 vcc, v15, v11
	s_waitcnt lgkmcnt(0)
	v_add_f32_e32 v0, v0, v2
	v_cndmask_b32_e32 v2, v10, v15, vcc
	v_lshlrev_b32_e32 v2, 2, v2
	ds_bpermute_b32 v2, v2, v0
	v_cmp_lt_i32_e32 vcc, v16, v11
	s_waitcnt lgkmcnt(0)
	v_add_f32_e32 v0, v0, v2
	v_cndmask_b32_e32 v2, v10, v16, vcc
	v_lshlrev_b32_e32 v2, 2, v2
	ds_bpermute_b32 v2, v2, v0
	v_cmp_lt_i32_e32 vcc, v17, v11
	s_waitcnt lgkmcnt(0)
	v_add_f32_e32 v0, v0, v2
	v_cndmask_b32_e32 v2, v10, v17, vcc
	v_lshlrev_b32_e32 v2, 2, v2
	ds_bpermute_b32 v2, v2, v0
	s_mov_b64 s[18:19], exec
	v_readlane_b32 s20, v251, 31
	v_readlane_b32 s21, v251, 32
	s_and_b64 s[20:21], s[18:19], s[20:21]
	s_mov_b64 exec, s[20:21]
	s_cbranch_execz .LBB0_444
	s_mov_b64 s[20:21], exec
	s_waitcnt lgkmcnt(0)
	v_add_f32_e32 v2, v0, v2
	v_bfrev_b32_e32 v0, 1

; #define SEAM(k) do { if (IN(k) && IN((k) + 1)) { if (FLAT_BARRIER) flat_barrier((unsigned*)(ws + WS_BAR) + 64); else xcd_barrier(bar); } } while (0)
; __global__ void __launch_bounds__(NWAVES * 64, 2) fwd_megakernel(Args args) {
;     ...
;     SEAM(3);
.LBB0_452:
	s_cmp_gt_i32 s67, 4
	s_cselect_b64 s[18:19], -1, 0
	s_and_b64 s[0:1], s[0:1], s[18:19]
	s_andn2_b64 vcc, exec, s[0:1]
	s_cbranch_vccnz .LBB0_506
	s_cmpk_lt_u32 s33, 224
	s_cbranch_scc1 .LBB0_506
	s_waitcnt vmcnt(0) lgkmcnt(0)
	s_barrier
	s_mov_b64 s[98:99], exec
	v_readlane_b32 s100, v251, 27
	v_readlane_b32 s101, v251, 28
	s_and_b64 s[100:101], s[98:99], s[100:101]
	s_mov_b64 exec, s[100:101]
	s_cbranch_execz .Lsig3_done
	s_add_u32 s100, s90, 0x3700
	s_addc_u32 s101, s91, 0
	v_mov_b32_e32 v16, 0
	v_mov_b32_e32 v0, 1
	global_atomic_add v16, v0, s[100:101]

; template <class Epi, class Sched, bool ALIGN_EPI = false, bool SP2 = false>
; __device__ __forceinline__ void gemm_phase(PG8_LAS unsigned char* lds, const Gemm g, const Sched& S, const Epi& E) {
;     ...
;     for (;;) {
;         const bool has_next = S.next(ui + 1, nxt);
;         const char* nA = has_next ? (const char*)g.A + (size_t)nxt.pm * tstep + (size_t)nxt.k0 * kstepA : cA; const char* nB = has_next ? (const char*)g.Bt + (size_t)nxt.pn * tstep + (size_t)nxt.k0 * kstepB : cB;
.LBB0_615:
	s_mov_b32 s99, 0
	s_cmp_lg_u32 s26, 32
	s_cbranch_scc1 .Lhf4
	s_mov_b32 s99, 1

; #define PG8_STAGE(bufoff, gbase, voff) do { _Pragma("unroll") for (int _i = 0; _i < 2; ++_i) \
;         __builtin_amdgcn_global_load_lds((const unsigned*)((const char*)(gbase) + (voff)[_i]), (PG8_LAS unsigned*)(lds + (bufoff) + ldsw + _i * 8192), 16, 0, 0); } while (0)
; #define PG8_LDA(dst, b, h) do { _Pragma("unroll") for (int m = 0; m < 4; ++m) _Pragma("unroll") for (int k = 0; k < 2; ++k) dst[m][k] = *(const PG8_LAS bf16x8*)(lds + PG8_SA(b, h) + aoff + m * 2048 + k * 1024); } while (0)
; #define PG8_LDB(dst, b, h) do { _Pragma("unroll") for (int n = 0; n < 2; ++n) _Pragma("unroll") for (int k = 0; k < 2; ++k) dst[n][k] = *(const PG8_LAS bf16x8*)(lds + PG8_SB(b, h) + boff + n * 2048 + k * 1024); } while (0)
; #define PG8_MMA(ai, bj, At, Bt) do { __builtin_amdgcn_s_setprio(1); _Pragma("unroll") for (int m = 0; m < 4; ++m) _Pragma("unroll") for (int n = 0; n < 2; ++n) _Pragma("unroll") for (int k = 0; k < 2; ++k) \
;         acc[ai][bj][m][n] = __builtin_amdgcn_mfma_f32_16x16x32_bf16(Bt[n][k], At[m][k], acc[ai][bj][m][n], 0, 0, 0); __builtin_amdgcn_s_setprio(0); } while (0)
; #define PG8_WAIT_V(n) asm volatile("s_waitcnt vmcnt(" #n ")" ::: "memory")
; #define PG8_WAIT_L(n) asm volatile("s_waitcnt lgkmcnt(" #n ")" ::: "memory")
; #define PG8_BAR __builtin_amdgcn_s_barrier()
; #define PG8_SCHED __builtin_amdgcn_sched_barrier(0)
; template <class Epi, class Sched, bool ALIGN_EPI = false, bool SP2 = false>
; __device__ __forceinline__ void gemm_phase(PG8_LAS unsigned char* lds, const Gemm g, const Sched& S, const Epi& E) {
;     ...
;             PG8_LDB(B0, 0, 0); PG8_LDB(B1, 0, 1); PG8_SCHED; PG8_LDA(At, 0, 0); PG8_STAGE(PG8_SA(1, 1), a1 + hstepA, voffA);
;             PG8_WAIT_V(8); PG8_WAIT_L(0); PG8_BAR; PG8_MMA(0, 0, At, B0); PG8_MMA(0, 1, At, B1); PG8_BAR; PG8_SCHED;
;             PG8_LDA(At, 0, 1); PG8_STAGE(PG8_SB(0, 0), b2, voffB); PG8_STAGE(PG8_SB(0, 1), b2 + hstepB, voffB); PG8_STAGE(PG8_SA(0, 0), a2, voffA);
;             PG8_WAIT_V(8); PG8_WAIT_L(0); PG8_BAR; PG8_MMA(1, 0, At, B0); PG8_MMA(1, 1, At, B1); PG8_BAR; PG8_SCHED;
.LBB0_616:
	s_sub_u32 s100, s38, 0x80000
	s_subb_u32 s101, s39, 0
	ds_read_b128 v[132:135], v147
	ds_read_b128 v[136:139], v147 offset:1024
	ds_read_b128 v[140:143], v147 offset:2048
	ds_read_b128 v[152:155], v147 offset:3072
	ds_read_b128 v[156:159], v148
	ds_read_b128 v[160:163], v148 offset:1024
	ds_read_b128 v[164:167], v148 offset:2048
	ds_read_b128 v[168:171], v148 offset:3072
	s_add_u32 s40, s38, 0xfff80080
	s_addc_u32 s41, s39, -1
	s_cmp_eq_u32 s55, 28
	s_cselect_b32 s43, s1, s41
	s_cselect_b32 s42, s27, s40
	s_cselect_b32 s41, s25, s54
	s_cselect_b32 s40, s37, s53
	ds_read_b128 v[172:175], v149
	ds_read_b128 v[176:179], v149 offset:1024
	ds_read_b128 v[180:183], v149 offset:2048
	ds_read_b128 v[204:207], v149 offset:3072
	ds_read_b128 v[208:211], v149 offset:4096
	ds_read_b128 v[212:215], v149 offset:5120
	ds_read_b128 v[216:219], v149 offset:6144
	ds_read_b128 v[220:223], v149 offset:7168
	s_mov_b32 m0, s48
	s_nop 0
	global_load_lds_dwordx4 v128, s[100:101]
	s_mov_b32 m0, s49
	s_nop 0
	global_load_lds_dwordx4 v130, s[100:101]
	s_add_i32 m0, s13, 0xc000
	s_nop 0
	global_load_lds_dwordx4 v128, s[38:39]
	s_add_i32 m0, s13, 0xe000
	s_nop 0
	global_load_lds_dwordx4 v130, s[38:39]
	s_waitcnt vmcnt(8)
	s_waitcnt lgkmcnt(0)
	s_setprio 1
	s_barrier
	v_mfma_f32_16x16x32_bf16 v[124:127], v[132:135], v[172:175], v[124:127]
	v_mfma_f32_16x16x32_bf16 v[120:123], v[140:143], v[172:175], v[120:123]
	v_mfma_f32_16x16x32_bf16 v[108:111], v[132:135], v[180:183], v[108:111]
	v_mfma_f32_16x16x32_bf16 v[104:107], v[140:143], v[180:183], v[104:107]
	v_mfma_f32_16x16x32_bf16 v[92:95], v[132:135], v[208:211], v[92:95]
	v_mfma_f32_16x16x32_bf16 v[88:91], v[140:143], v[208:211], v[88:91]
	v_mfma_f32_16x16x32_bf16 v[76:79], v[132:135], v[216:219], v[76:79]
	v_mfma_f32_16x16x32_bf16 v[72:75], v[140:143], v[216:219], v[72:75]
	v_mfma_f32_16x16x32_bf16 v[124:127], v[136:139], v[176:179], v[124:127]
	v_mfma_f32_16x16x32_bf16 v[120:123], v[152:155], v[176:179], v[120:123]
	v_mfma_f32_16x16x32_bf16 v[108:111], v[136:139], v[204:207], v[108:111]
	v_mfma_f32_16x16x32_bf16 v[104:107], v[152:155], v[204:207], v[104:107]
	v_mfma_f32_16x16x32_bf16 v[92:95], v[136:139], v[212:215], v[92:95]
	v_mfma_f32_16x16x32_bf16 v[88:91], v[152:155], v[212:215], v[88:91]
	v_mfma_f32_16x16x32_bf16 v[76:79], v[136:139], v[220:223], v[76:79]
	v_mfma_f32_16x16x32_bf16 v[72:75], v[152:155], v[220:223], v[72:75]
	v_mfma_f32_16x16x32_bf16 v[116:119], v[156:159], v[172:175], v[116:119]
	v_mfma_f32_16x16x32_bf16 v[112:115], v[164:167], v[172:175], v[112:115]
	v_mfma_f32_16x16x32_bf16 v[100:103], v[156:159], v[180:183], v[100:103]
	v_mfma_f32_16x16x32_bf16 v[96:99], v[164:167], v[180:183], v[96:99]
	v_mfma_f32_16x16x32_bf16 v[84:87], v[156:159], v[208:211], v[84:87]
	v_mfma_f32_16x16x32_bf16 v[80:83], v[164:167], v[208:211], v[80:83]
	v_mfma_f32_16x16x32_bf16 v[68:71], v[156:159], v[216:219], v[68:71]
	v_mfma_f32_16x16x32_bf16 v[64:67], v[164:167], v[216:219], v[64:67]
	v_mfma_f32_16x16x32_bf16 v[116:119], v[160:163], v[176:179], v[116:119]
	v_mfma_f32_16x16x32_bf16 v[112:115], v[168:171], v[176:179], v[112:115]
	v_mfma_f32_16x16x32_bf16 v[100:103], v[160:163], v[204:207], v[100:103]
	v_mfma_f32_16x16x32_bf16 v[96:99], v[168:171], v[204:207], v[96:99]
	v_mfma_f32_16x16x32_bf16 v[84:87], v[160:163], v[212:215], v[84:87]
	v_mfma_f32_16x16x32_bf16 v[80:83], v[168:171], v[212:215], v[80:83]
	v_mfma_f32_16x16x32_bf16 v[68:71], v[160:163], v[220:223], v[68:71]
	v_mfma_f32_16x16x32_bf16 v[64:67], v[168:171], v[220:223], v[64:67]
	s_barrier
	s_setprio 0
	s_add_i32 s56, s50, s2
	s_mov_b32 m0, s56
	ds_read_b128 v[172:175], v149 offset:16384
	ds_read_b128 v[176:179], v149 offset:17408
	ds_read_b128 v[180:183], v149 offset:18432
	ds_read_b128 v[204:207], v149 offset:19456
	ds_read_b128 v[208:211], v149 offset:20480
	ds_read_b128 v[212:215], v149 offset:21504
	ds_read_b128 v[216:219], v149 offset:22528
	ds_read_b128 v[220:223], v149 offset:23552
	global_load_lds_dwordx4 v194, s[40:41]
	s_add_i32 m0, s56, 0x2000
	s_add_u32 s56, s40, 0x4000
	s_addc_u32 s57, s41, 0
	s_add_i32 s58, s51, s2
	global_load_lds_dwordx4 v198, s[40:41]
	s_mov_b32 m0, s58
	s_nop 0
	global_load_lds_dwordx4 v194, s[56:57]
	s_add_i32 m0, s58, 0x2000
	s_nop 0
	global_load_lds_dwordx4 v198, s[56:57]
	s_waitcnt vmcnt(6)
	s_waitcnt lgkmcnt(0)
	s_setprio 1
	s_barrier
	v_mfma_f32_16x16x32_bf16 v[60:63], v[132:135], v[172:175], v[60:63]
	v_mfma_f32_16x16x32_bf16 v[56:59], v[140:143], v[172:175], v[56:59]
	v_mfma_f32_16x16x32_bf16 v[44:47], v[132:135], v[180:183], v[44:47]
	v_mfma_f32_16x16x32_bf16 v[40:43], v[140:143], v[180:183], v[40:43]
	v_mfma_f32_16x16x32_bf16 v[28:31], v[132:135], v[208:211], v[28:31]
	v_mfma_f32_16x16x32_bf16 v[24:27], v[140:143], v[208:211], v[24:27]
	v_mfma_f32_16x16x32_bf16 v[12:15], v[132:135], v[216:219], v[12:15]
	v_mfma_f32_16x16x32_bf16 v[8:11], v[140:143], v[216:219], v[8:11]
	v_mfma_f32_16x16x32_bf16 v[60:63], v[136:139], v[176:179], v[60:63]
	v_mfma_f32_16x16x32_bf16 v[56:59], v[152:155], v[176:179], v[56:59]
	v_mfma_f32_16x16x32_bf16 v[44:47], v[136:139], v[204:207], v[44:47]
	v_mfma_f32_16x16x32_bf16 v[40:43], v[152:155], v[204:207], v[40:43]
	v_mfma_f32_16x16x32_bf16 v[28:31], v[136:139], v[212:215], v[28:31]
	v_mfma_f32_16x16x32_bf16 v[24:27], v[152:155], v[212:215], v[24:27]
	v_mfma_f32_16x16x32_bf16 v[12:15], v[136:139], v[220:223], v[12:15]
	v_mfma_f32_16x16x32_bf16 v[8:11], v[152:155], v[220:223], v[8:11]
	v_mfma_f32_16x16x32_bf16 v[52:55], v[156:159], v[172:175], v[52:55]
	v_mfma_f32_16x16x32_bf16 v[48:51], v[164:167], v[172:175], v[48:51]
	v_mfma_f32_16x16x32_bf16 v[36:39], v[156:159], v[180:183], v[36:39]
	v_mfma_f32_16x16x32_bf16 v[32:35], v[164:167], v[180:183], v[32:35]
	v_mfma_f32_16x16x32_bf16 v[20:23], v[156:159], v[208:211], v[20:23]
	v_mfma_f32_16x16x32_bf16 v[16:19], v[164:167], v[208:211], v[16:19]
	v_mfma_f32_16x16x32_bf16 v[4:7], v[156:159], v[216:219], v[4:7]
	v_mfma_f32_16x16x32_bf16 v[0:3], v[164:167], v[216:219], v[0:3]
	v_mfma_f32_16x16x32_bf16 v[52:55], v[160:163], v[176:179], v[52:55]
	v_mfma_f32_16x16x32_bf16 v[48:51], v[168:171], v[176:179], v[48:51]
	v_mfma_f32_16x16x32_bf16 v[36:39], v[160:163], v[204:207], v[36:39]
	v_mfma_f32_16x16x32_bf16 v[32:35], v[168:171], v[204:207], v[32:35]
	v_mfma_f32_16x16x32_bf16 v[20:23], v[160:163], v[212:215], v[20:23]
	v_mfma_f32_16x16x32_bf16 v[16:19], v[168:171], v[212:215], v[16:19]
	v_mfma_f32_16x16x32_bf16 v[4:7], v[160:163], v[220:223], v[4:7]
	v_mfma_f32_16x16x32_bf16 v[0:3], v[168:171], v[220:223], v[0:3]
	s_barrier
; #define PG8_STAGE(bufoff, gbase, voff) do { _Pragma("unroll") for (int _i = 0; _i < 2; ++_i) \
;         __builtin_amdgcn_global_load_lds((const unsigned*)((const char*)(gbase) + (voff)[_i]), (PG8_LAS unsigned*)(lds + (bufoff) + ldsw + _i * 8192), 16, 0, 0); } while (0)
; #define PG8_LDA(dst, b, h) do { _Pragma("unroll") for (int m = 0; m < 4; ++m) _Pragma("unroll") for (int k = 0; k < 2; ++k) dst[m][k] = *(const PG8_LAS bf16x8*)(lds + PG8_SA(b, h) + aoff + m * 2048 + k * 1024); } while (0)
; #define PG8_LDB(dst, b, h) do { _Pragma("unroll") for (int n = 0; n < 2; ++n) _Pragma("unroll") for (int k = 0; k < 2; ++k) dst[n][k] = *(const PG8_LAS bf16x8*)(lds + PG8_SB(b, h) + boff + n * 2048 + k * 1024); } while (0)
; #define PG8_MMA(ai, bj, At, Bt) do { __builtin_amdgcn_s_setprio(1); _Pragma("unroll") for (int m = 0; m < 4; ++m) _Pragma("unroll") for (int n = 0; n < 2; ++n) _Pragma("unroll") for (int k = 0; k < 2; ++k) \
;         acc[ai][bj][m][n] = __builtin_amdgcn_mfma_f32_16x16x32_bf16(Bt[n][k], At[m][k], acc[ai][bj][m][n], 0, 0, 0); __builtin_amdgcn_s_setprio(0); } while (0)
; #define PG8_WAIT_V(n) asm volatile("s_waitcnt vmcnt(" #n ")" ::: "memory")
; #define PG8_WAIT_L(n) asm volatile("s_waitcnt lgkmcnt(" #n ")" ::: "memory")
; template <class Epi, class Sched, bool ALIGN_EPI = false, bool SP2 = false>
; __device__ __forceinline__ void gemm_phase(PG8_LAS unsigned char* lds, const Gemm g, const Sched& S, const Epi& E) {
;     ...
;         for (int t = 0; t < nt; t += 2) {
;             const bool last = (t == nt - 2);
;             const char* a1 = cA + (size_t)(t + 1) * kstepA;
;             const char* a2 = last ? nA : cA + (size_t)(t + 2) * kstepA; const char* b2 = last ? nB : cB + (size_t)(t + 2) * kstepB;
;             const char* a3 = a2 + kstepA; const char* b3 = b2 + kstepB;
;             if (last && has_next) S.a_ready(nxt);
;     ...
;             PG8_LDB(B0, 1, 0); PG8_LDB(B1, 1, 1); PG8_SCHED; PG8_LDA(At, 1, 0); PG8_STAGE(PG8_SA(0, 1), a2 + hstepA, voffA);
;             PG8_WAIT_V(8); PG8_WAIT_L(0); PG8_BAR; PG8_MMA(0, 0, At, B0); PG8_MMA(0, 1, At, B1); PG8_BAR; PG8_SCHED;
;             PG8_LDA(At, 1, 1); PG8_STAGE(PG8_SB(1, 0), b3, voffB); PG8_STAGE(PG8_SB(1, 1), b3 + hstepB, voffB); PG8_STAGE(PG8_SA(1, 0), a3, voffA);
;             PG8_WAIT_V(8); PG8_WAIT_L(0); PG8_BAR; PG8_MMA(1, 0, At, B0); PG8_MMA(1, 1, At, B1); PG8_BAR; PG8_SCHED;
	s_setprio 0
	s_add_i32 s56, 0, 0x18000
	v_add_u32_e32 v151, s56, v145
	s_add_i32 s57, 0, 0x1c000
	ds_read_b128 v[132:135], v151
	ds_read_b128 v[136:139], v151 offset:1024
	ds_read_b128 v[140:143], v151 offset:2048
	ds_read_b128 v[152:155], v151 offset:3072
	v_add_u32_e32 v151, s57, v145
	ds_read_b128 v[156:159], v151
	ds_read_b128 v[160:163], v151 offset:1024
	ds_read_b128 v[164:167], v151 offset:2048
	ds_read_b128 v[168:171], v151 offset:3072
	s_mov_b32 m0, s13
	s_nop 0
	global_load_lds_dwordx4 v192, s[42:43]
	s_mov_b32 m0, s14
	s_nop 0
	global_load_lds_dwordx4 v196, s[42:43]
	s_add_u32 s42, s42, 0x80000
	s_addc_u32 s43, s43, 0
	s_mov_b32 m0, s15
	ds_read_b128 v[172:175], v149 offset:32768
	ds_read_b128 v[176:179], v149 offset:33792
	ds_read_b128 v[180:183], v149 offset:34816
	ds_read_b128 v[204:207], v149 offset:35840
	ds_read_b128 v[208:211], v149 offset:36864
	ds_read_b128 v[212:215], v149 offset:37888
	ds_read_b128 v[216:219], v149 offset:38912
	ds_read_b128 v[220:223], v149 offset:39936
	global_load_lds_dwordx4 v192, s[42:43]
	s_mov_b32 m0, s44
	s_nop 0
	global_load_lds_dwordx4 v196, s[42:43]
	s_waitcnt vmcnt(8)
	s_waitcnt lgkmcnt(0)
	s_setprio 1
	s_barrier
	v_mfma_f32_16x16x32_bf16 v[124:127], v[132:135], v[172:175], v[124:127]
	v_mfma_f32_16x16x32_bf16 v[120:123], v[140:143], v[172:175], v[120:123]
	v_mfma_f32_16x16x32_bf16 v[108:111], v[132:135], v[180:183], v[108:111]
	v_mfma_f32_16x16x32_bf16 v[104:107], v[140:143], v[180:183], v[104:107]
	v_mfma_f32_16x16x32_bf16 v[92:95], v[132:135], v[208:211], v[92:95]
	v_mfma_f32_16x16x32_bf16 v[88:91], v[140:143], v[208:211], v[88:91]
	v_mfma_f32_16x16x32_bf16 v[76:79], v[132:135], v[216:219], v[76:79]
	v_mfma_f32_16x16x32_bf16 v[72:75], v[140:143], v[216:219], v[72:75]
	v_mfma_f32_16x16x32_bf16 v[124:127], v[136:139], v[176:179], v[124:127]
	v_mfma_f32_16x16x32_bf16 v[120:123], v[152:155], v[176:179], v[120:123]
	v_mfma_f32_16x16x32_bf16 v[108:111], v[136:139], v[204:207], v[108:111]
	v_mfma_f32_16x16x32_bf16 v[104:107], v[152:155], v[204:207], v[104:107]
	v_mfma_f32_16x16x32_bf16 v[92:95], v[136:139], v[212:215], v[92:95]
	v_mfma_f32_16x16x32_bf16 v[88:91], v[152:155], v[212:215], v[88:91]
	v_mfma_f32_16x16x32_bf16 v[76:79], v[136:139], v[220:223], v[76:79]
	v_mfma_f32_16x16x32_bf16 v[72:75], v[152:155], v[220:223], v[72:75]
	v_mfma_f32_16x16x32_bf16 v[116:119], v[156:159], v[172:175], v[116:119]
	v_mfma_f32_16x16x32_bf16 v[112:115], v[164:167], v[172:175], v[112:115]
	v_mfma_f32_16x16x32_bf16 v[100:103], v[156:159], v[180:183], v[100:103]
	v_mfma_f32_16x16x32_bf16 v[96:99], v[164:167], v[180:183], v[96:99]
	v_mfma_f32_16x16x32_bf16 v[84:87], v[156:159], v[208:211], v[84:87]
	v_mfma_f32_16x16x32_bf16 v[80:83], v[164:167], v[208:211], v[80:83]
	v_mfma_f32_16x16x32_bf16 v[68:71], v[156:159], v[216:219], v[68:71]
	v_mfma_f32_16x16x32_bf16 v[64:67], v[164:167], v[216:219], v[64:67]
	v_mfma_f32_16x16x32_bf16 v[116:119], v[160:163], v[176:179], v[116:119]
	v_mfma_f32_16x16x32_bf16 v[112:115], v[168:171], v[176:179], v[112:115]
	v_mfma_f32_16x16x32_bf16 v[100:103], v[160:163], v[204:207], v[100:103]
	v_mfma_f32_16x16x32_bf16 v[96:99], v[168:171], v[204:207], v[96:99]
	v_mfma_f32_16x16x32_bf16 v[84:87], v[160:163], v[212:215], v[84:87]
	v_mfma_f32_16x16x32_bf16 v[80:83], v[168:171], v[212:215], v[80:83]
	v_mfma_f32_16x16x32_bf16 v[68:71], v[160:163], v[220:223], v[68:71]
	v_mfma_f32_16x16x32_bf16 v[64:67], v[168:171], v[220:223], v[64:67]
	s_barrier
	s_setprio 0
	s_add_u32 s42, s40, 0x8000
	s_addc_u32 s43, s41, 0
	s_add_i32 s56, s56, s2
	s_mov_b32 m0, s56
	ds_read_b128 v[172:175], v149 offset:49152
	ds_read_b128 v[176:179], v149 offset:50176
	ds_read_b128 v[180:183], v149 offset:51200
	ds_read_b128 v[204:207], v149 offset:52224
	ds_read_b128 v[208:211], v149 offset:53248
	ds_read_b128 v[212:215], v149 offset:54272
	ds_read_b128 v[216:219], v149 offset:55296
	ds_read_b128 v[220:223], v149 offset:56320
	global_load_lds_dwordx4 v194, s[42:43]
	s_add_i32 m0, s56, 0x2000
	s_add_u32 s40, s40, 0xc000
	s_addc_u32 s41, s41, 0
	global_load_lds_dwordx4 v198, s[42:43]
	s_add_i32 s42, s57, s2
	s_mov_b32 m0, s42
	s_nop 0
	global_load_lds_dwordx4 v194, s[40:41]
	s_add_i32 m0, s42, 0x2000
	s_nop 0
	global_load_lds_dwordx4 v198, s[40:41]
	s_waitcnt vmcnt(6)
	s_waitcnt lgkmcnt(0)
	s_setprio 1
	s_barrier
	v_mfma_f32_16x16x32_bf16 v[60:63], v[132:135], v[172:175], v[60:63]
	v_mfma_f32_16x16x32_bf16 v[56:59], v[140:143], v[172:175], v[56:59]
	v_mfma_f32_16x16x32_bf16 v[44:47], v[132:135], v[180:183], v[44:47]
	v_mfma_f32_16x16x32_bf16 v[40:43], v[140:143], v[180:183], v[40:43]
	v_mfma_f32_16x16x32_bf16 v[28:31], v[132:135], v[208:211], v[28:31]
	v_mfma_f32_16x16x32_bf16 v[24:27], v[140:143], v[208:211], v[24:27]
	v_mfma_f32_16x16x32_bf16 v[12:15], v[132:135], v[216:219], v[12:15]
	v_mfma_f32_16x16x32_bf16 v[8:11], v[140:143], v[216:219], v[8:11]
	v_mfma_f32_16x16x32_bf16 v[60:63], v[136:139], v[176:179], v[60:63]
	v_mfma_f32_16x16x32_bf16 v[56:59], v[152:155], v[176:179], v[56:59]
	v_mfma_f32_16x16x32_bf16 v[44:47], v[136:139], v[204:207], v[44:47]
	v_mfma_f32_16x16x32_bf16 v[40:43], v[152:155], v[204:207], v[40:43]
	v_mfma_f32_16x16x32_bf16 v[28:31], v[136:139], v[212:215], v[28:31]
	v_mfma_f32_16x16x32_bf16 v[24:27], v[152:155], v[212:215], v[24:27]
	v_mfma_f32_16x16x32_bf16 v[12:15], v[136:139], v[220:223], v[12:15]
	v_mfma_f32_16x16x32_bf16 v[8:11], v[152:155], v[220:223], v[8:11]
	v_mfma_f32_16x16x32_bf16 v[52:55], v[156:159], v[172:175], v[52:55]
	v_mfma_f32_16x16x32_bf16 v[48:51], v[164:167], v[172:175], v[48:51]
	v_mfma_f32_16x16x32_bf16 v[36:39], v[156:159], v[180:183], v[36:39]
	v_mfma_f32_16x16x32_bf16 v[32:35], v[164:167], v[180:183], v[32:35]
	v_mfma_f32_16x16x32_bf16 v[20:23], v[156:159], v[208:211], v[20:23]
	v_mfma_f32_16x16x32_bf16 v[16:19], v[164:167], v[208:211], v[16:19]
	v_mfma_f32_16x16x32_bf16 v[4:7], v[156:159], v[216:219], v[4:7]
	v_mfma_f32_16x16x32_bf16 v[0:3], v[164:167], v[216:219], v[0:3]
	v_mfma_f32_16x16x32_bf16 v[52:55], v[160:163], v[176:179], v[52:55]
	v_mfma_f32_16x16x32_bf16 v[48:51], v[168:171], v[176:179], v[48:51]
	v_mfma_f32_16x16x32_bf16 v[36:39], v[160:163], v[204:207], v[36:39]
	v_mfma_f32_16x16x32_bf16 v[32:35], v[168:171], v[204:207], v[32:35]
	v_mfma_f32_16x16x32_bf16 v[20:23], v[160:163], v[212:215], v[20:23]
	v_mfma_f32_16x16x32_bf16 v[16:19], v[168:171], v[212:215], v[16:19]
	v_mfma_f32_16x16x32_bf16 v[4:7], v[160:163], v[220:223], v[4:7]
	v_mfma_f32_16x16x32_bf16 v[0:3], v[168:171], v[220:223], v[0:3]
	s_barrier
	s_setprio 0
	s_add_i32 s55, s55, 2
	s_add_u32 s53, s53, 0x10000
	s_addc_u32 s54, s54, 0
	s_add_u32 s38, s38, 0x100
	s_addc_u32 s39, s39, 0
	s_cmp_eq_u32 s99, 0
	s_cbranch_scc1 .Lml4_skip
	s_cmp_eq_u32 s55, 18
	s_cbranch_scc0 .Lml4_a
	s_add_u32 s100, s90, 0x3700
	s_addc_u32 s101, s91, 0
	v_mov_b32_e32 v227, 0
	global_load_dword v226, v227, s[100:101] sc1
	s_branch .Lml4_skip
; template <class Epi, class Sched, bool ALIGN_EPI = false, bool SP2 = false>
; __device__ __forceinline__ void gemm_phase(PG8_LAS unsigned char* lds, const Gemm g, const Sched& S, const Epi& E) {
;     ...
;         for (int t = 0; t < nt; t += 2) {
;             const bool last = (t == nt - 2);
;             const char* a1 = cA + (size_t)(t + 1) * kstepA;
;             const char* a2 = last ? nA : cA + (size_t)(t + 2) * kstepA; const char* b2 = last ? nB : cB + (size_t)(t + 2) * kstepB;
;             const char* a3 = a2 + kstepA; const char* b3 = b2 + kstepB;
;             if (last && has_next) S.a_ready(nxt);
.Lml4_a:
	s_cmp_eq_u32 s55, 24
	s_cbranch_scc0 .Lml4_skip
	s_waitcnt vmcnt(0)
	v_readfirstlane_b32 s98, v226
	s_cmpk_lt_u32 s98, 0x20
	s_cbranch_scc0 .Lml4_got
	s_add_u32 s100, s90, 0x3700
	s_addc_u32 s101, s91, 0
.Lml4_spin:
	global_load_dword v226, v227, s[100:101] sc1
	s_waitcnt vmcnt(0)
	v_readfirstlane_b32 s98, v226
	s_cmpk_lt_u32 s98, 0x20
	s_cbranch_scc0 .Lml4_got
	s_sleep 2
	s_branch .Lml4_spin
.Lml4_got:
	buffer_inv sc1
	s_mov_b32 s99, 0
.Lml4_skip:
	s_cmp_gt_u32 s55, 29
	s_cbranch_scc0 .LBB0_616
	s_and_b64 vcc, exec, s[22:23]
	s_cbranch_vccz .LBB0_619
	s_barrier

; __device__ __forceinline__ float bf_lo(unsigned w) { return __uint_as_float(w << 16); }
; __device__ __forceinline__ float bf_hi(unsigned w) { return __uint_as_float(w & 0xffff0000u); }
; template <int MODE> __device__ __forceinline__ void fix_resid(const float* part, int nsl, const float* xp, const float* xs, const float* meta, float* xbuf, bf16_t* xb, float* ss, float* out, int gw, int ngw, int lane) {
;     for (int it = gw; it < NTAIL * 8; it += ngw) {
;         const int rloc = it >> 3, row = TAIL0 + rloc, col = (it & 7) * 256 + lane * 4;
;         const bf16_t* p = (const bf16_t*)part + (size_t)rloc * 2048 + col;
;         f32x4_t v = (f32x4_t){0.f, 0.f, 0.f, 0.f};
; #pragma unroll 8
;         for (int s = 0; s < nsl; ++s) { const u32x2_t w = __builtin_nontemporal_load((const u32x2_t*)(p + (size_t)s * (256 * 2048))); v += (f32x4_t){bf_lo(w.x), bf_hi(w.x), bf_lo(w.y), bf_hi(w.y)}; }
;         const float scale = (MODE == 1) ? 1.0f : 0.5f;
;         const u32x2_t bw = *(const u32x2_t*)(xb + (size_t)row * DM + col);
.LBB0_1195:
	s_cmp_lt_i32 s66, 10
	s_cselect_b64 s[0:1], -1, 0
	s_and_b64 s[6:7], s[0:1], s[6:7]
	s_cmpk_gt_u32 s33, 239
	s_cselect_b64 s[0:1], -1, 0
	s_and_b64 s[0:1], s[6:7], s[0:1]
	s_andn2_b64 vcc, exec, s[0:1]
	s_cbranch_vccnz .LBB0_1205
	v_readlane_b32 s1, v251, 29
	v_mbcnt_hi_u32_b32 v8, -1, v201
	s_sub_i32 s0, s33, 240
	s_lshl_b32 s0, s0, 11
	s_lshl_b32 s1, s1, 8
	v_and_b32_e32 v0, 64, v8
	s_add_i32 s2, s0, s1
	s_mov_b32 s10, 0x8000
	s_waitcnt lgkmcnt(0)
	v_mov_b32_e32 v1, 0
	s_mov_b32 s12, 0x100000
	s_mov_b32 s13, 0x200000
	s_mov_b32 s14, 0x300000
	s_mov_b32 s15, 0x400000
	s_mov_b32 s18, 0x500000
	s_mov_b32 s19, 0x600000
	s_mov_b32 s20, 0x700000
	v_add_u32_e32 v9, 64, v0
	v_xor_b32_e32 v10, 1, v8
	v_xor_b32_e32 v11, 2, v8
	v_xor_b32_e32 v12, 4, v8
	v_xor_b32_e32 v13, 8, v8
	v_xor_b32_e32 v14, 16, v8
	v_xor_b32_e32 v15, 32, v8
	s_lshr_b32 s21, s2, 8
	s_branch .LBB0_1198
.LBB0_1197:
	s_or_b64 exec, exec, s[8:9]
	s_addk_i32 s21, 0x80
	s_add_i32 s2, s2, s10
	s_cmpk_lt_i32 s21, 0x600
	s_cbranch_scc0 .LBB0_1205
.LBB0_1198:
	s_lshl_b32 s0, s2, 1
	s_and_b32 s0, s0, 0xe00
	v_lshl_or_b32 v0, v241, 1, s0
	s_ashr_i32 s0, s21, 3
	s_ashr_i32 s1, s0, 31
	s_lshl_b64 s[8:9], s[0:1], 12
	s_add_u32 s8, s86, s8
	s_addc_u32 s9, s87, s9
	s_waitcnt lgkmcnt(0)
	v_mov_b32_e32 v2, 0
	v_mov_b32_e32 v3, v1
	v_mov_b32_e32 v4, 0
	v_mov_b32_e32 v5, v1
	global_load_dwordx2 v[44:45], v0, s[8:9] nt
	s_add_u32 s8, s8, 0x100000
	s_addc_u32 s9, s9, 0
	global_load_dwordx2 v[46:47], v0, s[8:9] nt
	s_add_u32 s8, s8, 0x100000
	s_addc_u32 s9, s9, 0
	global_load_dwordx2 v[48:49], v0, s[8:9] nt
	s_add_u32 s8, s8, 0x100000
	s_addc_u32 s9, s9, 0
	global_load_dwordx2 v[50:51], v0, s[8:9] nt
	s_add_u32 s8, s8, 0x100000
	s_addc_u32 s9, s9, 0
	global_load_dwordx2 v[52:53], v0, s[8:9] nt
	s_add_u32 s8, s8, 0x100000
	s_addc_u32 s9, s9, 0
	global_load_dwordx2 v[54:55], v0, s[8:9] nt
	s_add_u32 s8, s8, 0x100000
	s_addc_u32 s9, s9, 0
	global_load_dwordx2 v[56:57], v0, s[8:9] nt
	s_add_u32 s8, s8, 0x100000
	s_addc_u32 s9, s9, 0
	global_load_dwordx2 v[58:59], v0, s[8:9] nt
	s_add_u32 s8, s8, 0x100000
	s_addc_u32 s9, s9, 0
	global_load_dwordx2 v[60:61], v0, s[8:9] nt
	s_add_u32 s8, s8, 0x100000
	s_addc_u32 s9, s9, 0
	global_load_dwordx2 v[62:63], v0, s[8:9] nt
	s_add_u32 s8, s8, 0x100000
	s_addc_u32 s9, s9, 0
	global_load_dwordx2 v[64:65], v0, s[8:9] nt
	s_add_u32 s8, s8, 0x100000
	s_addc_u32 s9, s9, 0
	global_load_dwordx2 v[66:67], v0, s[8:9] nt
	s_add_u32 s8, s8, 0x100000
	s_addc_u32 s9, s9, 0
	global_load_dwordx2 v[68:69], v0, s[8:9] nt
	s_add_u32 s8, s8, 0x100000
	s_addc_u32 s9, s9, 0
	global_load_dwordx2 v[70:71], v0, s[8:9] nt
	s_add_u32 s8, s8, 0x100000
	s_addc_u32 s9, s9, 0
	global_load_dwordx2 v[72:73], v0, s[8:9] nt
	s_add_u32 s8, s8, 0x100000
	s_addc_u32 s9, s9, 0
	global_load_dwordx2 v[74:75], v0, s[8:9] nt
	s_lshl_b32 s1, s21, 8
	s_and_b32 s1, s1, 0x700
	s_addk_i32 s0, 0x2000
	v_or_b32_e32 v0, s1, v241
	s_ashr_i32 s1, s0, 31
	s_lshl_b64 s[8:9], s[0:1], 12
	s_add_u32 s8, s96, s8
	s_addc_u32 s9, s97, s9
	v_lshlrev_b32_e32 v18, 1, v0
	global_load_dwordx2 v[6:7], v18, s[8:9]
	s_waitcnt vmcnt(9)
	v_lshlrev_b32_e32 v16, 16, v44
	v_and_b32_e32 v17, 0xffff0000, v44
	v_lshlrev_b32_e32 v20, 16, v45
	v_and_b32_e32 v21, 0xffff0000, v45
	v_pk_add_f32 v[2:3], v[2:3], v[16:17]
	v_pk_add_f32 v[4:5], v[4:5], v[20:21]
	v_lshlrev_b32_e32 v16, 16, v46
	v_and_b32_e32 v17, 0xffff0000, v46
	v_lshlrev_b32_e32 v20, 16, v47
	v_and_b32_e32 v21, 0xffff0000, v47
	v_pk_add_f32 v[2:3], v[2:3], v[16:17]
	v_pk_add_f32 v[4:5], v[4:5], v[20:21]
	v_lshlrev_b32_e32 v16, 16, v48
	v_and_b32_e32 v17, 0xffff0000, v48
	v_lshlrev_b32_e32 v20, 16, v49
	v_and_b32_e32 v21, 0xffff0000, v49
	v_pk_add_f32 v[2:3], v[2:3], v[16:17]
	v_pk_add_f32 v[4:5], v[4:5], v[20:21]
	v_lshlrev_b32_e32 v16, 16, v50
	v_and_b32_e32 v17, 0xffff0000, v50
	v_lshlrev_b32_e32 v20, 16, v51
	v_and_b32_e32 v21, 0xffff0000, v51
	v_pk_add_f32 v[2:3], v[2:3], v[16:17]
	v_pk_add_f32 v[4:5], v[4:5], v[20:21]
	v_lshlrev_b32_e32 v16, 16, v52
	v_and_b32_e32 v17, 0xffff0000, v52
	v_lshlrev_b32_e32 v20, 16, v53
	v_and_b32_e32 v21, 0xffff0000, v53
	v_pk_add_f32 v[2:3], v[2:3], v[16:17]
	v_pk_add_f32 v[4:5], v[4:5], v[20:21]
	v_lshlrev_b32_e32 v16, 16, v54
	v_and_b32_e32 v17, 0xffff0000, v54
	v_lshlrev_b32_e32 v20, 16, v55
	v_and_b32_e32 v21, 0xffff0000, v55
	v_pk_add_f32 v[2:3], v[2:3], v[16:17]
	v_pk_add_f32 v[4:5], v[4:5], v[20:21]
	v_lshlrev_b32_e32 v16, 16, v56
	v_and_b32_e32 v17, 0xffff0000, v56
	v_lshlrev_b32_e32 v20, 16, v57
	v_and_b32_e32 v21, 0xffff0000, v57
	v_pk_add_f32 v[2:3], v[2:3], v[16:17]
	v_pk_add_f32 v[4:5], v[4:5], v[20:21]
	v_lshlrev_b32_e32 v16, 16, v58
	v_and_b32_e32 v17, 0xffff0000, v58
	v_lshlrev_b32_e32 v20, 16, v59
	v_and_b32_e32 v21, 0xffff0000, v59
	v_pk_add_f32 v[2:3], v[2:3], v[16:17]
	v_pk_add_f32 v[4:5], v[4:5], v[20:21]
	s_waitcnt vmcnt(1)
; __device__ __forceinline__ float bf_lo(unsigned w) { return __uint_as_float(w << 16); }
; __device__ __forceinline__ float bf_hi(unsigned w) { return __uint_as_float(w & 0xffff0000u); }
; __device__ __forceinline__ unsigned pk2(float lo, float hi) { return pg8::cvt_pk_bf16(lo, hi); }
; template <int MODE> __device__ __forceinline__ void fix_resid(const float* part, int nsl, const float* xp, const float* xs, const float* meta, float* xbuf, bf16_t* xb, float* ss, float* out, int gw, int ngw, int lane) {
;     ...
;         for (int s = 0; s < nsl; ++s) { const u32x2_t w = __builtin_nontemporal_load((const u32x2_t*)(p + (size_t)s * (256 * 2048))); v += (f32x4_t){bf_lo(w.x), bf_hi(w.x), bf_lo(w.y), bf_hi(w.y)}; }
;         const float scale = (MODE == 1) ? 1.0f : 0.5f;
;         const u32x2_t bw = *(const u32x2_t*)(xb + (size_t)row * DM + col);
;         const f32x4_t o = (f32x4_t){bf_lo(bw.x), bf_hi(bw.x), bf_lo(bw.y), bf_hi(bw.y)} + v * scale;
;         if (MODE == 2) { float* dst = y_row(out, row); if (dst) __builtin_nontemporal_store(o, (f32x4_t*)(dst + col)); }
;         else {
;             u32x2_t w; w.x = pk2(o.x, o.y); w.y = pk2(o.z, o.w); *(u32x2_t*)(xb + (size_t)row * DM + col) = w;
;             const float sq = wave_sum((o.x * o.x + o.y * o.y) + (o.z * o.z + o.w * o.w));
;             if (lane == 0) __hip_atomic_fetch_add(ss + row, sq, __ATOMIC_RELAXED, __HIP_MEMORY_SCOPE_AGENT);
;         }
	v_lshlrev_b32_e32 v16, 16, v60
	v_and_b32_e32 v17, 0xffff0000, v60
	v_lshlrev_b32_e32 v20, 16, v61
	v_and_b32_e32 v21, 0xffff0000, v61
	v_pk_add_f32 v[2:3], v[2:3], v[16:17]
	v_pk_add_f32 v[4:5], v[4:5], v[20:21]
	v_lshlrev_b32_e32 v16, 16, v62
	v_and_b32_e32 v17, 0xffff0000, v62
	v_lshlrev_b32_e32 v20, 16, v63
	v_and_b32_e32 v21, 0xffff0000, v63
	v_pk_add_f32 v[2:3], v[2:3], v[16:17]
	v_pk_add_f32 v[4:5], v[4:5], v[20:21]
	v_lshlrev_b32_e32 v16, 16, v64
	v_and_b32_e32 v17, 0xffff0000, v64
	v_lshlrev_b32_e32 v20, 16, v65
	v_and_b32_e32 v21, 0xffff0000, v65
	v_pk_add_f32 v[2:3], v[2:3], v[16:17]
	v_pk_add_f32 v[4:5], v[4:5], v[20:21]
	v_lshlrev_b32_e32 v16, 16, v66
	v_and_b32_e32 v17, 0xffff0000, v66
	v_lshlrev_b32_e32 v20, 16, v67
	v_and_b32_e32 v21, 0xffff0000, v67
	v_pk_add_f32 v[2:3], v[2:3], v[16:17]
	v_pk_add_f32 v[4:5], v[4:5], v[20:21]
	v_lshlrev_b32_e32 v16, 16, v68
	v_and_b32_e32 v17, 0xffff0000, v68
	v_lshlrev_b32_e32 v20, 16, v69
	v_and_b32_e32 v21, 0xffff0000, v69
	v_pk_add_f32 v[2:3], v[2:3], v[16:17]
	v_pk_add_f32 v[4:5], v[4:5], v[20:21]
	v_lshlrev_b32_e32 v16, 16, v70
	v_and_b32_e32 v17, 0xffff0000, v70
	v_lshlrev_b32_e32 v20, 16, v71
	v_and_b32_e32 v21, 0xffff0000, v71
	v_pk_add_f32 v[2:3], v[2:3], v[16:17]
	v_pk_add_f32 v[4:5], v[4:5], v[20:21]
	v_lshlrev_b32_e32 v16, 16, v72
	v_and_b32_e32 v17, 0xffff0000, v72
	v_lshlrev_b32_e32 v20, 16, v73
	v_and_b32_e32 v21, 0xffff0000, v73
	v_pk_add_f32 v[2:3], v[2:3], v[16:17]
	v_pk_add_f32 v[4:5], v[4:5], v[20:21]
	v_lshlrev_b32_e32 v16, 16, v74
	v_and_b32_e32 v17, 0xffff0000, v74
	v_lshlrev_b32_e32 v20, 16, v75
	v_and_b32_e32 v21, 0xffff0000, v75
	v_pk_add_f32 v[2:3], v[2:3], v[16:17]
	v_pk_add_f32 v[4:5], v[4:5], v[20:21]
	v_cmp_lt_i32_e32 vcc, v10, v9
	s_waitcnt vmcnt(0)
	v_lshlrev_b32_e32 v16, 16, v6
	v_and_b32_e32 v17, 0xffff0000, v6
	v_lshlrev_b32_e32 v6, 16, v7
	v_and_b32_e32 v7, 0xffff0000, v7
	v_pk_add_f32 v[4:5], v[4:5], v[6:7]
	v_pk_add_f32 v[6:7], v[2:3], v[16:17]
	v_mul_f32_e32 v3, v5, v5
	v_mul_f32_e32 v2, v7, v7
	v_cndmask_b32_e32 v0, v8, v10, vcc
	v_fmac_f32_e32 v2, v6, v6
	v_fmac_f32_e32 v3, v4, v4
	v_lshlrev_b32_e32 v0, 2, v0
	v_add_f32_e32 v2, v2, v3
	ds_bpermute_b32 v0, v0, v2
	v_cmp_lt_i32_e32 vcc, v11, v9
	v_cvt_pk_bf16_f32 v6, v6, v7
	v_cvt_pk_bf16_f32 v7, v4, v5
	global_store_dwordx2 v18, v[6:7], s[8:9] sc0 sc1
	s_waitcnt lgkmcnt(0)
	v_add_f32_e32 v0, v2, v0
	v_cndmask_b32_e32 v3, v8, v11, vcc
	v_lshlrev_b32_e32 v3, 2, v3
	ds_bpermute_b32 v2, v3, v0
	v_cmp_lt_i32_e32 vcc, v12, v9
	s_waitcnt lgkmcnt(0)
	v_add_f32_e32 v0, v0, v2
	v_cndmask_b32_e32 v3, v8, v12, vcc
	v_lshlrev_b32_e32 v3, 2, v3
	ds_bpermute_b32 v2, v3, v0
	v_cmp_lt_i32_e32 vcc, v13, v9
	s_waitcnt lgkmcnt(0)
	v_add_f32_e32 v0, v0, v2
	v_cndmask_b32_e32 v3, v8, v13, vcc
	v_lshlrev_b32_e32 v3, 2, v3
	ds_bpermute_b32 v2, v3, v0
	v_cmp_lt_i32_e32 vcc, v14, v9
	s_waitcnt lgkmcnt(0)
	v_add_f32_e32 v0, v0, v2
	v_cndmask_b32_e32 v3, v8, v14, vcc
	v_lshlrev_b32_e32 v3, 2, v3
	ds_bpermute_b32 v2, v3, v0
	v_cmp_lt_i32_e32 vcc, v15, v9
	s_waitcnt lgkmcnt(0)
	v_add_f32_e32 v0, v0, v2
	v_cndmask_b32_e32 v3, v8, v15, vcc
	v_lshlrev_b32_e32 v2, 2, v3
	ds_bpermute_b32 v2, v2, v0
	s_mov_b64 s[8:9], exec
	v_readlane_b32 s16, v251, 31
	v_readlane_b32 s17, v251, 32
	s_and_b64 s[16:17], s[8:9], s[16:17]
	s_mov_b64 exec, s[16:17]
	s_cbranch_execz .LBB0_1197
	s_mov_b64 s[16:17], exec
	s_waitcnt lgkmcnt(0)
	v_add_f32_e32 v2, v0, v2
	v_bfrev_b32_e32 v0, 1

; #define SEAM(k) do { if (IN(k) && IN((k) + 1)) { if (FLAT_BARRIER) flat_barrier((unsigned*)(ws + WS_BAR) + 64); else xcd_barrier(bar); } } while (0)
; __global__ void __launch_bounds__(NWAVES * 64, 2) fwd_megakernel(Args args) {
;     ...
;     SEAM(9);
.LBB0_1205:
	s_cmp_gt_i32 s67, 10
	s_cselect_b64 s[0:1], -1, 0
	s_and_b64 s[6:7], s[6:7], s[0:1]
	s_andn2_b64 vcc, exec, s[6:7]
	s_cbranch_vccnz .LBB0_1259
	s_cmpk_lt_u32 s33, 240
	s_cbranch_scc1 .LBB0_1259
	s_waitcnt vmcnt(0) lgkmcnt(0)
	s_barrier
	s_mov_b64 s[98:99], exec
	v_readlane_b32 s100, v251, 27
	v_readlane_b32 s101, v251, 28
	s_and_b64 s[100:101], s[98:99], s[100:101]
	s_mov_b64 exec, s[100:101]
	s_cbranch_execz .Lsig9_done
	s_add_u32 s100, s90, 0x3900
	s_addc_u32 s101, s91, 0
	v_mov_b32_e32 v16, 0
	v_mov_b32_e32 v0, 1
	global_atomic_add v16, v0, s[100:101]

; template <class Epi, class Sched, bool ALIGN_EPI = false, bool SP2 = false>
; __device__ __forceinline__ void gemm_phase(PG8_LAS unsigned char* lds, const Gemm g, const Sched& S, const Epi& E) {
;     ...
;     for (;;) {
;         const bool has_next = S.next(ui + 1, nxt);
;         const char* nA = has_next ? (const char*)g.A + (size_t)nxt.pm * tstep + (size_t)nxt.k0 * kstepA : cA; const char* nB = has_next ? (const char*)g.Bt + (size_t)nxt.pn * tstep + (size_t)nxt.k0 * kstepB : cB;
.LBB0_1338:
	s_mov_b32 s99, 0
	s_cmp_lg_u32 s22, 32
	s_cbranch_scc1 .Lhf10
	s_mov_b32 s99, 1

; #define PG8_STAGE(bufoff, gbase, voff) do { _Pragma("unroll") for (int _i = 0; _i < 2; ++_i) \
;         __builtin_amdgcn_global_load_lds((const unsigned*)((const char*)(gbase) + (voff)[_i]), (PG8_LAS unsigned*)(lds + (bufoff) + ldsw + _i * 8192), 16, 0, 0); } while (0)
; #define PG8_LDA(dst, b, h) do { _Pragma("unroll") for (int m = 0; m < 4; ++m) _Pragma("unroll") for (int k = 0; k < 2; ++k) dst[m][k] = *(const PG8_LAS bf16x8*)(lds + PG8_SA(b, h) + aoff + m * 2048 + k * 1024); } while (0)
; #define PG8_LDB(dst, b, h) do { _Pragma("unroll") for (int n = 0; n < 2; ++n) _Pragma("unroll") for (int k = 0; k < 2; ++k) dst[n][k] = *(const PG8_LAS bf16x8*)(lds + PG8_SB(b, h) + boff + n * 2048 + k * 1024); } while (0)
; #define PG8_MMA(ai, bj, At, Bt) do { __builtin_amdgcn_s_setprio(1); _Pragma("unroll") for (int m = 0; m < 4; ++m) _Pragma("unroll") for (int n = 0; n < 2; ++n) _Pragma("unroll") for (int k = 0; k < 2; ++k) \
;         acc[ai][bj][m][n] = __builtin_amdgcn_mfma_f32_16x16x32_bf16(Bt[n][k], At[m][k], acc[ai][bj][m][n], 0, 0, 0); __builtin_amdgcn_s_setprio(0); } while (0)
; #define PG8_WAIT_V(n) asm volatile("s_waitcnt vmcnt(" #n ")" ::: "memory")
; #define PG8_WAIT_L(n) asm volatile("s_waitcnt lgkmcnt(" #n ")" ::: "memory")
; #define PG8_BAR __builtin_amdgcn_s_barrier()
; #define PG8_SCHED __builtin_amdgcn_sched_barrier(0)
; template <class Epi, class Sched, bool ALIGN_EPI = false, bool SP2 = false>
; __device__ __forceinline__ void gemm_phase(PG8_LAS unsigned char* lds, const Gemm g, const Sched& S, const Epi& E) {
;     ...
;             PG8_LDB(B0, 0, 0); PG8_LDB(B1, 0, 1); PG8_SCHED; PG8_LDA(At, 0, 0); PG8_STAGE(PG8_SA(1, 1), a1 + hstepA, voffA);
;             PG8_WAIT_V(8); PG8_WAIT_L(0); PG8_BAR; PG8_MMA(0, 0, At, B0); PG8_MMA(0, 1, At, B1); PG8_BAR; PG8_SCHED;
;             PG8_LDA(At, 0, 1); PG8_STAGE(PG8_SB(0, 0), b2, voffB); PG8_STAGE(PG8_SB(0, 1), b2 + hstepB, voffB); PG8_STAGE(PG8_SA(0, 0), a2, voffA);
;             PG8_WAIT_V(8); PG8_WAIT_L(0); PG8_BAR; PG8_MMA(1, 0, At, B0); PG8_MMA(1, 1, At, B1); PG8_BAR; PG8_SCHED;
.LBB0_1339:
	s_sub_u32 s100, s34, 0x80000
	s_subb_u32 s101, s35, 0
	ds_read_b128 v[136:139], v129
	ds_read_b128 v[144:147], v129 offset:1024
	ds_read_b128 v[148:151], v129 offset:2048
	ds_read_b128 v[152:155], v129 offset:3072
	ds_read_b128 v[156:159], v141
	ds_read_b128 v[160:163], v141 offset:1024
	ds_read_b128 v[164:167], v141 offset:2048
	ds_read_b128 v[168:171], v141 offset:3072
	s_add_u32 s36, s34, 0xfff80080
	s_addc_u32 s37, s35, -1
	s_cmp_eq_u32 s53, 28
	s_cselect_b32 s39, s23, s37
	s_cselect_b32 s38, s49, s36
	s_cselect_b32 s37, s21, s52
	s_cselect_b32 s36, s50, s51
	ds_read_b128 v[172:175], v142
	ds_read_b128 v[176:179], v142 offset:1024
	ds_read_b128 v[180:183], v142 offset:2048
	ds_read_b128 v[184:187], v142 offset:3072
	ds_read_b128 v[188:191], v142 offset:4096
	ds_read_b128 v[204:207], v142 offset:5120
	ds_read_b128 v[208:211], v142 offset:6144
	ds_read_b128 v[212:215], v142 offset:7168
	s_mov_b32 m0, s43
	s_nop 0
	global_load_lds_dwordx4 v132, s[100:101]
	s_mov_b32 m0, s44
	s_nop 0
	global_load_lds_dwordx4 v134, s[100:101]
	s_add_i32 m0, s15, 0xc000
	s_nop 0
	global_load_lds_dwordx4 v132, s[34:35]
	s_add_i32 m0, s15, 0xe000
	s_nop 0
	global_load_lds_dwordx4 v134, s[34:35]
	s_waitcnt vmcnt(8)
	s_waitcnt lgkmcnt(0)
	s_setprio 1
	s_barrier
	v_mfma_f32_16x16x32_bf16 v[124:127], v[136:139], v[172:175], v[124:127]
	v_mfma_f32_16x16x32_bf16 v[120:123], v[148:151], v[172:175], v[120:123]
	v_mfma_f32_16x16x32_bf16 v[108:111], v[136:139], v[180:183], v[108:111]
	v_mfma_f32_16x16x32_bf16 v[104:107], v[148:151], v[180:183], v[104:107]
	v_mfma_f32_16x16x32_bf16 v[92:95], v[136:139], v[188:191], v[92:95]
	v_mfma_f32_16x16x32_bf16 v[88:91], v[148:151], v[188:191], v[88:91]
	v_mfma_f32_16x16x32_bf16 v[76:79], v[136:139], v[208:211], v[76:79]
	v_mfma_f32_16x16x32_bf16 v[72:75], v[148:151], v[208:211], v[72:75]
	v_mfma_f32_16x16x32_bf16 v[124:127], v[144:147], v[176:179], v[124:127]
	v_mfma_f32_16x16x32_bf16 v[120:123], v[152:155], v[176:179], v[120:123]
	v_mfma_f32_16x16x32_bf16 v[108:111], v[144:147], v[184:187], v[108:111]
	v_mfma_f32_16x16x32_bf16 v[104:107], v[152:155], v[184:187], v[104:107]
	v_mfma_f32_16x16x32_bf16 v[92:95], v[144:147], v[204:207], v[92:95]
	v_mfma_f32_16x16x32_bf16 v[88:91], v[152:155], v[204:207], v[88:91]
	v_mfma_f32_16x16x32_bf16 v[76:79], v[144:147], v[212:215], v[76:79]
	v_mfma_f32_16x16x32_bf16 v[72:75], v[152:155], v[212:215], v[72:75]
	v_mfma_f32_16x16x32_bf16 v[116:119], v[156:159], v[172:175], v[116:119]
	v_mfma_f32_16x16x32_bf16 v[112:115], v[164:167], v[172:175], v[112:115]
	v_mfma_f32_16x16x32_bf16 v[100:103], v[156:159], v[180:183], v[100:103]
	v_mfma_f32_16x16x32_bf16 v[96:99], v[164:167], v[180:183], v[96:99]
	v_mfma_f32_16x16x32_bf16 v[84:87], v[156:159], v[188:191], v[84:87]
	v_mfma_f32_16x16x32_bf16 v[80:83], v[164:167], v[188:191], v[80:83]
	v_mfma_f32_16x16x32_bf16 v[68:71], v[156:159], v[208:211], v[68:71]
	v_mfma_f32_16x16x32_bf16 v[64:67], v[164:167], v[208:211], v[64:67]
	v_mfma_f32_16x16x32_bf16 v[116:119], v[160:163], v[176:179], v[116:119]
	v_mfma_f32_16x16x32_bf16 v[112:115], v[168:171], v[176:179], v[112:115]
	v_mfma_f32_16x16x32_bf16 v[100:103], v[160:163], v[184:187], v[100:103]
	v_mfma_f32_16x16x32_bf16 v[96:99], v[168:171], v[184:187], v[96:99]
	v_mfma_f32_16x16x32_bf16 v[84:87], v[160:163], v[204:207], v[84:87]
	v_mfma_f32_16x16x32_bf16 v[80:83], v[168:171], v[204:207], v[80:83]
	v_mfma_f32_16x16x32_bf16 v[68:71], v[160:163], v[212:215], v[68:71]
	v_mfma_f32_16x16x32_bf16 v[64:67], v[168:171], v[212:215], v[64:67]
	s_barrier
	s_setprio 0
	s_add_i32 s54, s46, s2
	s_mov_b32 m0, s54
	ds_read_b128 v[172:175], v142 offset:16384
	ds_read_b128 v[176:179], v142 offset:17408
	ds_read_b128 v[180:183], v142 offset:18432
	ds_read_b128 v[184:187], v142 offset:19456
	ds_read_b128 v[188:191], v142 offset:20480
	ds_read_b128 v[204:207], v142 offset:21504
	ds_read_b128 v[208:211], v142 offset:22528
	ds_read_b128 v[212:215], v142 offset:23552
	global_load_lds_dwordx4 v194, s[36:37]
	s_add_i32 m0, s54, 0x2000
	s_add_u32 s54, s36, 0x4000
	s_addc_u32 s55, s37, 0
	s_add_i32 s56, s47, s2
	global_load_lds_dwordx4 v198, s[36:37]
	s_mov_b32 m0, s56
	s_nop 0
	global_load_lds_dwordx4 v194, s[54:55]
	s_add_i32 m0, s56, 0x2000
	s_nop 0
	global_load_lds_dwordx4 v198, s[54:55]
	s_waitcnt vmcnt(6)
	s_waitcnt lgkmcnt(0)
	s_setprio 1
	s_barrier
	v_mfma_f32_16x16x32_bf16 v[60:63], v[136:139], v[172:175], v[60:63]
	v_mfma_f32_16x16x32_bf16 v[56:59], v[148:151], v[172:175], v[56:59]
	v_mfma_f32_16x16x32_bf16 v[44:47], v[136:139], v[180:183], v[44:47]
	v_mfma_f32_16x16x32_bf16 v[40:43], v[148:151], v[180:183], v[40:43]
	v_mfma_f32_16x16x32_bf16 v[28:31], v[136:139], v[188:191], v[28:31]
	v_mfma_f32_16x16x32_bf16 v[24:27], v[148:151], v[188:191], v[24:27]
	v_mfma_f32_16x16x32_bf16 v[12:15], v[136:139], v[208:211], v[12:15]
	v_mfma_f32_16x16x32_bf16 v[8:11], v[148:151], v[208:211], v[8:11]
	v_mfma_f32_16x16x32_bf16 v[60:63], v[144:147], v[176:179], v[60:63]
	v_mfma_f32_16x16x32_bf16 v[56:59], v[152:155], v[176:179], v[56:59]
	v_mfma_f32_16x16x32_bf16 v[44:47], v[144:147], v[184:187], v[44:47]
	v_mfma_f32_16x16x32_bf16 v[40:43], v[152:155], v[184:187], v[40:43]
	v_mfma_f32_16x16x32_bf16 v[28:31], v[144:147], v[204:207], v[28:31]
	v_mfma_f32_16x16x32_bf16 v[24:27], v[152:155], v[204:207], v[24:27]
	v_mfma_f32_16x16x32_bf16 v[12:15], v[144:147], v[212:215], v[12:15]
	v_mfma_f32_16x16x32_bf16 v[8:11], v[152:155], v[212:215], v[8:11]
	v_mfma_f32_16x16x32_bf16 v[52:55], v[156:159], v[172:175], v[52:55]
	v_mfma_f32_16x16x32_bf16 v[48:51], v[164:167], v[172:175], v[48:51]
	v_mfma_f32_16x16x32_bf16 v[36:39], v[156:159], v[180:183], v[36:39]
	v_mfma_f32_16x16x32_bf16 v[32:35], v[164:167], v[180:183], v[32:35]
	v_mfma_f32_16x16x32_bf16 v[20:23], v[156:159], v[188:191], v[20:23]
	v_mfma_f32_16x16x32_bf16 v[16:19], v[164:167], v[188:191], v[16:19]
	v_mfma_f32_16x16x32_bf16 v[4:7], v[156:159], v[208:211], v[4:7]
	v_mfma_f32_16x16x32_bf16 v[0:3], v[164:167], v[208:211], v[0:3]
	v_mfma_f32_16x16x32_bf16 v[52:55], v[160:163], v[176:179], v[52:55]
	v_mfma_f32_16x16x32_bf16 v[48:51], v[168:171], v[176:179], v[48:51]
	v_mfma_f32_16x16x32_bf16 v[36:39], v[160:163], v[184:187], v[36:39]
	v_mfma_f32_16x16x32_bf16 v[32:35], v[168:171], v[184:187], v[32:35]
	v_mfma_f32_16x16x32_bf16 v[20:23], v[160:163], v[204:207], v[20:23]
	v_mfma_f32_16x16x32_bf16 v[16:19], v[168:171], v[204:207], v[16:19]
	v_mfma_f32_16x16x32_bf16 v[4:7], v[160:163], v[212:215], v[4:7]
	v_mfma_f32_16x16x32_bf16 v[0:3], v[168:171], v[212:215], v[0:3]
	s_barrier
; #define PG8_STAGE(bufoff, gbase, voff) do { _Pragma("unroll") for (int _i = 0; _i < 2; ++_i) \
;         __builtin_amdgcn_global_load_lds((const unsigned*)((const char*)(gbase) + (voff)[_i]), (PG8_LAS unsigned*)(lds + (bufoff) + ldsw + _i * 8192), 16, 0, 0); } while (0)
; #define PG8_LDA(dst, b, h) do { _Pragma("unroll") for (int m = 0; m < 4; ++m) _Pragma("unroll") for (int k = 0; k < 2; ++k) dst[m][k] = *(const PG8_LAS bf16x8*)(lds + PG8_SA(b, h) + aoff + m * 2048 + k * 1024); } while (0)
; #define PG8_LDB(dst, b, h) do { _Pragma("unroll") for (int n = 0; n < 2; ++n) _Pragma("unroll") for (int k = 0; k < 2; ++k) dst[n][k] = *(const PG8_LAS bf16x8*)(lds + PG8_SB(b, h) + boff + n * 2048 + k * 1024); } while (0)
; #define PG8_MMA(ai, bj, At, Bt) do { __builtin_amdgcn_s_setprio(1); _Pragma("unroll") for (int m = 0; m < 4; ++m) _Pragma("unroll") for (int n = 0; n < 2; ++n) _Pragma("unroll") for (int k = 0; k < 2; ++k) \
;         acc[ai][bj][m][n] = __builtin_amdgcn_mfma_f32_16x16x32_bf16(Bt[n][k], At[m][k], acc[ai][bj][m][n], 0, 0, 0); __builtin_amdgcn_s_setprio(0); } while (0)
; #define PG8_WAIT_V(n) asm volatile("s_waitcnt vmcnt(" #n ")" ::: "memory")
; #define PG8_WAIT_L(n) asm volatile("s_waitcnt lgkmcnt(" #n ")" ::: "memory")
; #define PG8_BAR __builtin_amdgcn_s_barrier()
; #define PG8_SCHED __builtin_amdgcn_sched_barrier(0)
; template <class Epi, class Sched, bool ALIGN_EPI = false, bool SP2 = false>
; __device__ __forceinline__ void gemm_phase(PG8_LAS unsigned char* lds, const Gemm g, const Sched& S, const Epi& E) {
;     ...
;             PG8_LDB(B0, 1, 0); PG8_LDB(B1, 1, 1); PG8_SCHED; PG8_LDA(At, 1, 0); PG8_STAGE(PG8_SA(0, 1), a2 + hstepA, voffA);
;             PG8_WAIT_V(8); PG8_WAIT_L(0); PG8_BAR; PG8_MMA(0, 0, At, B0); PG8_MMA(0, 1, At, B1); PG8_BAR; PG8_SCHED;
;             PG8_LDA(At, 1, 1); PG8_STAGE(PG8_SB(1, 0), b3, voffB); PG8_STAGE(PG8_SB(1, 1), b3 + hstepB, voffB); PG8_STAGE(PG8_SA(1, 0), a3, voffA);
;             PG8_WAIT_V(8); PG8_WAIT_L(0); PG8_BAR; PG8_MMA(1, 0, At, B0); PG8_MMA(1, 1, At, B1); PG8_BAR; PG8_SCHED;
	s_setprio 0
	s_add_i32 s54, 0, 0x18000
	s_add_i32 s55, 0, 0x1c000
	v_add_u32_e32 v152, s54, v140
	v_add_u32_e32 v168, s55, v140
	ds_read_b128 v[136:139], v152
	ds_read_b128 v[144:147], v152 offset:1024
	ds_read_b128 v[148:151], v152 offset:2048
	ds_read_b128 v[152:155], v152 offset:3072
	ds_read_b128 v[156:159], v168
	ds_read_b128 v[160:163], v168 offset:1024
	ds_read_b128 v[164:167], v168 offset:2048
	ds_read_b128 v[168:171], v168 offset:3072
	s_mov_b32 m0, s15
	s_nop 0
	global_load_lds_dwordx4 v192, s[38:39]
	s_mov_b32 m0, s40
	s_nop 0
	global_load_lds_dwordx4 v196, s[38:39]
	s_add_u32 s38, s38, 0x80000
	s_addc_u32 s39, s39, 0
	s_mov_b32 m0, s41
	ds_read_b128 v[172:175], v142 offset:32768
	ds_read_b128 v[176:179], v142 offset:33792
	ds_read_b128 v[180:183], v142 offset:34816
	ds_read_b128 v[184:187], v142 offset:35840
	ds_read_b128 v[188:191], v142 offset:36864
	ds_read_b128 v[204:207], v142 offset:37888
	ds_read_b128 v[208:211], v142 offset:38912
	ds_read_b128 v[212:215], v142 offset:39936
	global_load_lds_dwordx4 v192, s[38:39]
	s_mov_b32 m0, s42
	s_nop 0
	global_load_lds_dwordx4 v196, s[38:39]
	s_waitcnt vmcnt(8)
	s_waitcnt lgkmcnt(0)
	s_setprio 1
	s_barrier
	v_mfma_f32_16x16x32_bf16 v[124:127], v[136:139], v[172:175], v[124:127]
	v_mfma_f32_16x16x32_bf16 v[120:123], v[148:151], v[172:175], v[120:123]
	v_mfma_f32_16x16x32_bf16 v[108:111], v[136:139], v[180:183], v[108:111]
	v_mfma_f32_16x16x32_bf16 v[104:107], v[148:151], v[180:183], v[104:107]
	v_mfma_f32_16x16x32_bf16 v[92:95], v[136:139], v[188:191], v[92:95]
	v_mfma_f32_16x16x32_bf16 v[88:91], v[148:151], v[188:191], v[88:91]
	v_mfma_f32_16x16x32_bf16 v[76:79], v[136:139], v[208:211], v[76:79]
	v_mfma_f32_16x16x32_bf16 v[72:75], v[148:151], v[208:211], v[72:75]
	v_mfma_f32_16x16x32_bf16 v[124:127], v[144:147], v[176:179], v[124:127]
	v_mfma_f32_16x16x32_bf16 v[120:123], v[152:155], v[176:179], v[120:123]
	v_mfma_f32_16x16x32_bf16 v[108:111], v[144:147], v[184:187], v[108:111]
	v_mfma_f32_16x16x32_bf16 v[104:107], v[152:155], v[184:187], v[104:107]
	v_mfma_f32_16x16x32_bf16 v[92:95], v[144:147], v[204:207], v[92:95]
	v_mfma_f32_16x16x32_bf16 v[88:91], v[152:155], v[204:207], v[88:91]
	v_mfma_f32_16x16x32_bf16 v[76:79], v[144:147], v[212:215], v[76:79]
	v_mfma_f32_16x16x32_bf16 v[72:75], v[152:155], v[212:215], v[72:75]
	v_mfma_f32_16x16x32_bf16 v[116:119], v[156:159], v[172:175], v[116:119]
	v_mfma_f32_16x16x32_bf16 v[112:115], v[164:167], v[172:175], v[112:115]
	v_mfma_f32_16x16x32_bf16 v[100:103], v[156:159], v[180:183], v[100:103]
	v_mfma_f32_16x16x32_bf16 v[96:99], v[164:167], v[180:183], v[96:99]
	v_mfma_f32_16x16x32_bf16 v[84:87], v[156:159], v[188:191], v[84:87]
	v_mfma_f32_16x16x32_bf16 v[80:83], v[164:167], v[188:191], v[80:83]
	v_mfma_f32_16x16x32_bf16 v[68:71], v[156:159], v[208:211], v[68:71]
	v_mfma_f32_16x16x32_bf16 v[64:67], v[164:167], v[208:211], v[64:67]
	v_mfma_f32_16x16x32_bf16 v[116:119], v[160:163], v[176:179], v[116:119]
	v_mfma_f32_16x16x32_bf16 v[112:115], v[168:171], v[176:179], v[112:115]
	v_mfma_f32_16x16x32_bf16 v[100:103], v[160:163], v[184:187], v[100:103]
	v_mfma_f32_16x16x32_bf16 v[96:99], v[168:171], v[184:187], v[96:99]
	v_mfma_f32_16x16x32_bf16 v[84:87], v[160:163], v[204:207], v[84:87]
	v_mfma_f32_16x16x32_bf16 v[80:83], v[168:171], v[204:207], v[80:83]
	v_mfma_f32_16x16x32_bf16 v[68:71], v[160:163], v[212:215], v[68:71]
	v_mfma_f32_16x16x32_bf16 v[64:67], v[168:171], v[212:215], v[64:67]
	s_barrier
	s_setprio 0
	s_add_u32 s38, s36, 0x8000
	s_addc_u32 s39, s37, 0
	s_add_i32 s54, s54, s2
	s_mov_b32 m0, s54
	ds_read_b128 v[172:175], v142 offset:49152
	ds_read_b128 v[176:179], v142 offset:50176
	ds_read_b128 v[180:183], v142 offset:51200
	ds_read_b128 v[184:187], v142 offset:52224
	ds_read_b128 v[188:191], v142 offset:53248
	ds_read_b128 v[204:207], v142 offset:54272
	ds_read_b128 v[208:211], v142 offset:55296
	ds_read_b128 v[212:215], v142 offset:56320
	global_load_lds_dwordx4 v194, s[38:39]
	s_add_i32 m0, s54, 0x2000
	s_add_u32 s36, s36, 0xc000
	s_addc_u32 s37, s37, 0
	global_load_lds_dwordx4 v198, s[38:39]
	s_add_i32 s38, s55, s2
	s_mov_b32 m0, s38
	s_nop 0
	global_load_lds_dwordx4 v194, s[36:37]
	s_add_i32 m0, s38, 0x2000
	s_nop 0
	global_load_lds_dwordx4 v198, s[36:37]
	s_waitcnt vmcnt(6)
	s_waitcnt lgkmcnt(0)
	s_setprio 1
	s_barrier
	v_mfma_f32_16x16x32_bf16 v[60:63], v[136:139], v[172:175], v[60:63]
	v_mfma_f32_16x16x32_bf16 v[56:59], v[148:151], v[172:175], v[56:59]
	v_mfma_f32_16x16x32_bf16 v[44:47], v[136:139], v[180:183], v[44:47]
	v_mfma_f32_16x16x32_bf16 v[40:43], v[148:151], v[180:183], v[40:43]
	v_mfma_f32_16x16x32_bf16 v[28:31], v[136:139], v[188:191], v[28:31]
	v_mfma_f32_16x16x32_bf16 v[24:27], v[148:151], v[188:191], v[24:27]
	v_mfma_f32_16x16x32_bf16 v[12:15], v[136:139], v[208:211], v[12:15]
	v_mfma_f32_16x16x32_bf16 v[8:11], v[148:151], v[208:211], v[8:11]
	v_mfma_f32_16x16x32_bf16 v[60:63], v[144:147], v[176:179], v[60:63]
	v_mfma_f32_16x16x32_bf16 v[56:59], v[152:155], v[176:179], v[56:59]
	v_mfma_f32_16x16x32_bf16 v[44:47], v[144:147], v[184:187], v[44:47]
	v_mfma_f32_16x16x32_bf16 v[40:43], v[152:155], v[184:187], v[40:43]
	v_mfma_f32_16x16x32_bf16 v[28:31], v[144:147], v[204:207], v[28:31]
	v_mfma_f32_16x16x32_bf16 v[24:27], v[152:155], v[204:207], v[24:27]
	v_mfma_f32_16x16x32_bf16 v[12:15], v[144:147], v[212:215], v[12:15]
	v_mfma_f32_16x16x32_bf16 v[8:11], v[152:155], v[212:215], v[8:11]
	v_mfma_f32_16x16x32_bf16 v[52:55], v[156:159], v[172:175], v[52:55]
	v_mfma_f32_16x16x32_bf16 v[48:51], v[164:167], v[172:175], v[48:51]
	v_mfma_f32_16x16x32_bf16 v[36:39], v[156:159], v[180:183], v[36:39]
	v_mfma_f32_16x16x32_bf16 v[32:35], v[164:167], v[180:183], v[32:35]
	v_mfma_f32_16x16x32_bf16 v[20:23], v[156:159], v[188:191], v[20:23]
	v_mfma_f32_16x16x32_bf16 v[16:19], v[164:167], v[188:191], v[16:19]
	v_mfma_f32_16x16x32_bf16 v[4:7], v[156:159], v[208:211], v[4:7]
	v_mfma_f32_16x16x32_bf16 v[0:3], v[164:167], v[208:211], v[0:3]
	v_mfma_f32_16x16x32_bf16 v[52:55], v[160:163], v[176:179], v[52:55]
	v_mfma_f32_16x16x32_bf16 v[48:51], v[168:171], v[176:179], v[48:51]
	v_mfma_f32_16x16x32_bf16 v[36:39], v[160:163], v[184:187], v[36:39]
	v_mfma_f32_16x16x32_bf16 v[32:35], v[168:171], v[184:187], v[32:35]
	v_mfma_f32_16x16x32_bf16 v[20:23], v[160:163], v[204:207], v[20:23]
	v_mfma_f32_16x16x32_bf16 v[16:19], v[168:171], v[204:207], v[16:19]
	v_mfma_f32_16x16x32_bf16 v[4:7], v[160:163], v[212:215], v[4:7]
	v_mfma_f32_16x16x32_bf16 v[0:3], v[168:171], v[212:215], v[0:3]
	s_barrier
	s_setprio 0
	s_add_i32 s53, s53, 2
	s_add_u32 s51, s51, 0x10000
	s_addc_u32 s52, s52, 0
	s_add_u32 s34, s34, 0x100
	s_addc_u32 s35, s35, 0
	s_cmp_eq_u32 s99, 0
	s_cbranch_scc1 .Lml10_skip
	s_cmp_eq_u32 s53, 18
	s_cbranch_scc0 .Lml10_a
	s_add_u32 s100, s90, 0x3900
	s_addc_u32 s101, s91, 0
	v_mov_b32_e32 v227, 0
	global_load_dword v226, v227, s[100:101] sc1
	s_branch .Lml10_skip
; template <class Epi, class Sched, bool ALIGN_EPI = false, bool SP2 = false>
; __device__ __forceinline__ void gemm_phase(PG8_LAS unsigned char* lds, const Gemm g, const Sched& S, const Epi& E) {
;     ...
;         for (int t = 0; t < nt; t += 2) {
;             const bool last = (t == nt - 2);
;             const char* a1 = cA + (size_t)(t + 1) * kstepA;
;             const char* a2 = last ? nA : cA + (size_t)(t + 2) * kstepA; const char* b2 = last ? nB : cB + (size_t)(t + 2) * kstepB;
;             const char* a3 = a2 + kstepA; const char* b3 = b2 + kstepB;
;             if (last && has_next) S.a_ready(nxt);
.Lml10_a:
	s_cmp_eq_u32 s53, 24
	s_cbranch_scc0 .Lml10_skip
	s_waitcnt vmcnt(0)
	v_readfirstlane_b32 s98, v226
	s_cmpk_lt_u32 s98, 0x10
	s_cbranch_scc0 .Lml10_got
	s_add_u32 s100, s90, 0x3900
	s_addc_u32 s101, s91, 0
.Lml10_spin:
	global_load_dword v226, v227, s[100:101] sc1
	s_waitcnt vmcnt(0)
	v_readfirstlane_b32 s98, v226
	s_cmpk_lt_u32 s98, 0x10
	s_cbranch_scc0 .Lml10_got
	s_sleep 2
	s_branch .Lml10_spin

; #define PG8_BAR __builtin_amdgcn_s_barrier()
; template <class Epi, class Sched, bool ALIGN_EPI = false, bool SP2 = false>
; __device__ __forceinline__ void gemm_phase(PG8_LAS unsigned char* lds, const Gemm g, const Sched& S, const Epi& E) {
;     ...
;         for (int t = 0; t < nt; t += 2) {
;     ...
;         if constexpr (ALIGN_EPI) { if (wr == 0) PG8_BAR; }
;         if constexpr (!Epi::AFTER_DRAIN) { if (cur.part < 0) E(acc, cur, wr, wc, fr, fq); else store_part<Epi::PERM>(acc, cur, g.part, wr, wc, fr, fq); S.done(cur); }
.Lml10_skip:
	s_cmp_gt_u32 s53, 29
	s_cbranch_scc0 .LBB0_1339
	s_and_b64 vcc, exec, s[18:19]
	s_cbranch_vccz .LBB0_1342
	s_barrier
